# v15: + SWA attention rewrite (window-mask shortcuts), residual epilogue pipelined, rope table in LDS
# speedup vs baseline: 1.0410x; 1.0050x over previous
.LBB0_55:
	v_sub_u32_e64 v1, s40, v232 clamp
	s_min_u32 s30, s40, 0xe80
	s_addk_i32 s30, 0x180
	v_readfirstlane_b32 s31, v1
	s_lshr_b32 s35, s31, 6
	s_lshr_b32 s36, s30, 6
	s_and_b64 s[30:31], s[28:29], exec
	s_cselect_b32 s30, s41, s36
	s_cselect_b32 s40, 0, s35
	s_waitcnt vmcnt(0) lgkmcnt(0)
	s_barrier
	v_mov_b32_e32 v30, v0
	s_sub_i32 s41, s30, s40
	v_mov_b32_e32 v29, v0
	v_mov_b32_e32 v28, v0
	v_mov_b32_e32 v27, v0
	v_mov_b32_e32 v26, v0
	v_mov_b32_e32 v25, v0
	v_mov_b32_e32 v24, v0
	v_mov_b32_e32 v23, v0
	v_mov_b32_e32 v22, v0
	v_mov_b32_e32 v21, v0
	v_mov_b32_e32 v20, v0
	v_mov_b32_e32 v19, v0
	v_mov_b32_e32 v18, v0
	v_mov_b32_e32 v17, v0
	v_mov_b32_e32 v16, v0
	v_mov_b32_e32 v15, v0
	v_mov_b32_e32 v14, v0
	v_mov_b32_e32 v13, v0
	v_mov_b32_e32 v12, v0
	v_mov_b32_e32 v11, v0
	v_mov_b32_e32 v10, v0
	v_mov_b32_e32 v9, v0
	v_mov_b32_e32 v8, v0
	v_mov_b32_e32 v7, v0
	v_mov_b32_e32 v6, v0
	v_mov_b32_e32 v5, v0
	v_mov_b32_e32 v4, v0
	v_mov_b32_e32 v3, v0
	v_mov_b32_e32 v2, v0
	v_mov_b32_e32 v1, v0
	v_mov_b64_e32 v[62:63], v[30:31]
	s_cmp_gt_i32 s41, -4
	v_mov_b32_e32 v121, v113
	v_mov_b64_e32 v[32:33], v[0:1]
	v_mov_b64_e32 v[60:61], v[28:29]
	v_mov_b64_e32 v[58:59], v[26:27]
	v_mov_b64_e32 v[56:57], v[24:25]
	v_mov_b64_e32 v[54:55], v[22:23]
	v_mov_b64_e32 v[52:53], v[20:21]
	v_mov_b64_e32 v[50:51], v[18:19]
	v_mov_b64_e32 v[48:49], v[16:17]
	v_mov_b64_e32 v[46:47], v[14:15]
	v_mov_b64_e32 v[44:45], v[12:13]
	v_mov_b64_e32 v[42:43], v[10:11]
	v_mov_b64_e32 v[40:41], v[8:9]
	v_mov_b64_e32 v[38:39], v[6:7]
	v_mov_b64_e32 v[36:37], v[4:5]
	v_mov_b64_e32 v[34:35], v[2:3]
	s_cbranch_scc0 .LBB0_38
	s_lshl_b32 s42, s42, 12
	s_lshl_b32 s30, s43, 8
	s_add_i32 s41, s41, 4
	s_addk_i32 s42, 0xff00
	s_sub_i32 s30, 0, s30
	s_and_b64 s[28:29], s[28:29], exec
	s_cselect_b32 s28, 0xfffff000, s30
	s_lshl_b32 s29, s44, 7
	v_add_u32_e32 v123, s29, v112
	v_add_u32_e32 v125, s29, v114
	s_lshl_b32 s29, s40, 6
	s_add_i32 s29, s29, s28
	v_mov_b32_e32 v1, v0
	v_mov_b32_e32 v2, v0
	v_mov_b32_e32 v3, v0
	v_mov_b32_e32 v4, v0
	v_mov_b32_e32 v5, v0
	v_mov_b32_e32 v6, v0
	v_mov_b32_e32 v7, v0
	v_mov_b32_e32 v8, v0
	v_mov_b32_e32 v9, v0
	v_mov_b32_e32 v10, v0
	v_mov_b32_e32 v11, v0
	v_mov_b32_e32 v12, v0
	v_mov_b32_e32 v13, v0
	v_mov_b32_e32 v14, v0
	v_mov_b32_e32 v15, v0
	v_mov_b32_e32 v16, v0
	v_mov_b32_e32 v17, v0
	v_mov_b32_e32 v18, v0
	v_mov_b32_e32 v19, v0
	v_mov_b32_e32 v20, v0
	v_mov_b32_e32 v21, v0
	v_mov_b32_e32 v22, v0
	v_mov_b32_e32 v23, v0
	v_mov_b32_e32 v24, v0
	v_mov_b32_e32 v25, v0
	v_mov_b32_e32 v26, v0
	v_mov_b32_e32 v27, v0
	v_mov_b32_e32 v28, v0
	v_mov_b32_e32 v29, v0
	v_mov_b32_e32 v30, v0
	v_mov_b32_e32 v31, v0
	s_waitcnt vmcnt(0)
	v_mul_f32_e32 v131, 0x3fb8aa3b, v64
	v_sub_f32_e32 v154, 0, v131
	v_mov_b32_e32 v155, v154
	v_mov_b32_e32 v156, v154
	v_mov_b32_e32 v157, v154
	v_mov_b32_e32 v158, v154
	v_mov_b32_e32 v159, v154
	v_mov_b32_e32 v160, v154
	v_mov_b32_e32 v161, v154
	v_mov_b32_e32 v162, v154
	v_mov_b32_e32 v163, v154
	v_mov_b32_e32 v164, v154
	v_mov_b32_e32 v165, v154
	v_mov_b32_e32 v166, v154
	v_mov_b32_e32 v167, v154
	v_mov_b32_e32 v168, v154
	v_mov_b32_e32 v169, v154
	s_mov_b32 s43, 0
	v_add_u32_e32 v127, s29, v134
	s_add_i32 s44, s34, 0x80
	s_mov_b32 s45, 2
	s_mov_b32 s46, 1
	v_mov_b32_e32 v121, v113
	s_mov_b32 s48, 0
	s_mov_b32 s47, 0

.LBB0_70:
	s_cmp_lt_u32 s47, 4
	s_cbranch_scc1 .Latt_swa_nomasktest
	v_add_u32_e32 v48, s43, v127
	v_add_u32_e32 v49, 0xfffffe7f, v48
	v_add_u32_e32 v50, 0xfffffeb6, v48
	v_cmp_lt_u32_e64 s[30:31], s50, v49
	v_cmp_lt_u32_e32 vcc, s50, v50
	s_nop 3
	s_or_b64 s[36:37], s[30:31], vcc
	s_cmp_eq_u64 s[36:37], 0
	s_cbranch_scc1 .Latt_swa_skip
	s_and_b64 s[36:37], s[30:31], vcc
.Latt_swa_nomasktest:
	s_mul_i32 s34, s48, 0x2400
	v_add_u32_e32 v208, s34, v115
	ds_read_b128 v[210:213], v208 offset:0
	ds_read_b128 v[214:217], v208 offset:4608
	ds_read_b128 v[218:221], v208 offset:32
	ds_read_b128 v[222:225], v208 offset:4640
	ds_read_b128 v[226:229], v208 offset:64
	ds_read_b128 v[238:241], v208 offset:4672
	ds_read_b128 v[242:245], v208 offset:96
	ds_read_b128 v[246:249], v208 offset:4704
	s_mul_i32 s34, s48, 0x2400
	v_add_u32_e32 v209, s34, v133
	s_waitcnt lgkmcnt(7)
	v_mfma_f32_32x32x16_bf16 v[64:79], v[210:213], v[96:99], v[154:169]
	s_waitcnt lgkmcnt(6)
	v_mfma_f32_32x32x16_bf16 v[32:47], v[214:217], v[96:99], v[154:169]
	s_waitcnt lgkmcnt(5)
	v_mfma_f32_32x32x16_bf16 v[64:79], v[218:221], v[100:103], v[64:79]
	s_waitcnt lgkmcnt(4)
	v_mfma_f32_32x32x16_bf16 v[32:47], v[222:225], v[100:103], v[32:47]
	s_waitcnt lgkmcnt(3)
	v_mfma_f32_32x32x16_bf16 v[64:79], v[226:229], v[104:107], v[64:79]
	s_waitcnt lgkmcnt(2)
	v_mfma_f32_32x32x16_bf16 v[32:47], v[238:241], v[104:107], v[32:47]
	s_waitcnt lgkmcnt(1)
	v_mfma_f32_32x32x16_bf16 v[64:79], v[242:245], v[108:111], v[64:79]
	s_waitcnt lgkmcnt(0)
	v_mfma_f32_32x32x16_bf16 v[32:47], v[246:249], v[108:111], v[32:47]
	ds_read_b128 v[210:213], v209 offset:27648
	ds_read_b128 v[214:217], v209 offset:32256
	ds_read_b128 v[218:221], v209 offset:27680
	ds_read_b128 v[222:225], v209 offset:32288
	ds_read_b128 v[226:229], v209 offset:27712
	ds_read_b128 v[238:241], v209 offset:32320
	ds_read_b128 v[242:245], v209 offset:27744
	ds_read_b128 v[246:249], v209 offset:32352
	s_nop 2
	s_nop 0
	s_cmp_lt_u32 s47, 4
	s_cbranch_scc1 .Latt_swa_nomask
	s_cmp_eq_u64 s[36:37], exec
	s_cbranch_scc1 .Latt_swa_nomask
	v_add_u32_e32 v48, s43, v127
	v_add_u32_e32 v49, 0xfffffe7f, v48
	v_cmp_lt_u32_e32 vcc, s50, v49
	v_add_u32_e32 v49, 0xfffffe9f, v48
	s_nop 0
	v_cndmask_b32_e32 v64, v233, v64, vcc
	v_cmp_lt_u32_e32 vcc, s50, v49
	v_add_u32_e32 v49, 0xfffffe80, v48
	s_nop 0
	v_cndmask_b32_e32 v32, v233, v32, vcc
	v_cmp_lt_u32_e32 vcc, s50, v49
	v_add_u32_e32 v49, 0xfffffea0, v48
	s_nop 0
	v_cndmask_b32_e32 v65, v233, v65, vcc
	v_cmp_lt_u32_e32 vcc, s50, v49
	v_add_u32_e32 v49, 0xfffffe81, v48
	s_nop 0
	v_cndmask_b32_e32 v33, v233, v33, vcc
	v_cmp_lt_u32_e32 vcc, s50, v49
	v_add_u32_e32 v49, 0xfffffea1, v48
	s_nop 0
	v_cndmask_b32_e32 v66, v233, v66, vcc
	v_cmp_lt_u32_e32 vcc, s50, v49
	v_add_u32_e32 v49, 0xfffffe82, v48
	s_nop 0
	v_cndmask_b32_e32 v34, v233, v34, vcc
	v_cmp_lt_u32_e32 vcc, s50, v49
	v_add_u32_e32 v49, 0xfffffea2, v48
	s_nop 0
	v_cndmask_b32_e32 v67, v233, v67, vcc
	v_cmp_lt_u32_e32 vcc, s50, v49
	v_add_u32_e32 v49, 0xfffffe83, v48
	s_nop 0
	v_cndmask_b32_e32 v35, v233, v35, vcc
	v_cmp_lt_u32_e32 vcc, s50, v49
	v_add_u32_e32 v49, 0xfffffea3, v48
	s_nop 0
	v_cndmask_b32_e32 v68, v233, v68, vcc
	v_cmp_lt_u32_e32 vcc, s50, v49
	v_add_u32_e32 v49, 0xfffffe84, v48
	s_nop 0
	v_cndmask_b32_e32 v36, v233, v36, vcc
	v_cmp_lt_u32_e32 vcc, s50, v49
	v_add_u32_e32 v49, 0xfffffea4, v48
	s_nop 0
	v_cndmask_b32_e32 v69, v233, v69, vcc
	v_cmp_lt_u32_e32 vcc, s50, v49
	v_add_u32_e32 v49, 0xfffffe85, v48
	s_nop 0
	v_cndmask_b32_e32 v37, v233, v37, vcc
	v_cmp_lt_u32_e32 vcc, s50, v49
	v_add_u32_e32 v49, 0xfffffea5, v48
	s_nop 0
	v_cndmask_b32_e32 v70, v233, v70, vcc
	v_cmp_lt_u32_e32 vcc, s50, v49
	v_add_u32_e32 v49, 0xfffffe86, v48
	s_nop 0
	v_cndmask_b32_e32 v38, v233, v38, vcc
	v_cmp_lt_u32_e32 vcc, s50, v49
	v_add_u32_e32 v49, 0xfffffea6, v48
	s_nop 0
	v_cndmask_b32_e32 v71, v233, v71, vcc
	v_cmp_lt_u32_e32 vcc, s50, v49
	v_add_u32_e32 v49, 0xfffffe8f, v48
	s_nop 0
	v_cndmask_b32_e32 v39, v233, v39, vcc
	v_cmp_lt_u32_e32 vcc, s50, v49
	v_add_u32_e32 v49, 0xfffffeaf, v48
	s_nop 0
	v_cndmask_b32_e32 v72, v233, v72, vcc
	v_cmp_lt_u32_e32 vcc, s50, v49
	v_add_u32_e32 v49, 0xfffffe90, v48
	s_nop 0
	v_cndmask_b32_e32 v40, v233, v40, vcc
	v_cmp_lt_u32_e32 vcc, s50, v49
	v_add_u32_e32 v49, 0xfffffeb0, v48
	s_nop 0
	v_cndmask_b32_e32 v73, v233, v73, vcc
	v_cmp_lt_u32_e32 vcc, s50, v49
	v_add_u32_e32 v49, 0xfffffe91, v48
	s_nop 0
	v_cndmask_b32_e32 v41, v233, v41, vcc
	v_cmp_lt_u32_e32 vcc, s50, v49
	v_add_u32_e32 v49, 0xfffffeb1, v48
	s_nop 0
	v_cndmask_b32_e32 v74, v233, v74, vcc
	v_cmp_lt_u32_e32 vcc, s50, v49
	v_add_u32_e32 v49, 0xfffffe92, v48
	s_nop 0
	v_cndmask_b32_e32 v42, v233, v42, vcc
	v_cmp_lt_u32_e32 vcc, s50, v49
	v_add_u32_e32 v49, 0xfffffeb2, v48
	s_nop 0
	v_cndmask_b32_e32 v75, v233, v75, vcc
	v_cmp_lt_u32_e32 vcc, s50, v49
	v_add_u32_e32 v49, 0xfffffe93, v48
	s_nop 0
	v_cndmask_b32_e32 v43, v233, v43, vcc
	v_cmp_lt_u32_e32 vcc, s50, v49
	v_add_u32_e32 v49, 0xfffffeb3, v48
	s_nop 0
	v_cndmask_b32_e32 v76, v233, v76, vcc
	v_cmp_lt_u32_e32 vcc, s50, v49
	v_add_u32_e32 v49, 0xfffffe94, v48
	s_nop 0
	v_cndmask_b32_e32 v44, v233, v44, vcc
	v_cmp_lt_u32_e32 vcc, s50, v49
	v_add_u32_e32 v49, 0xfffffeb4, v48
	s_nop 0
	v_cndmask_b32_e32 v77, v233, v77, vcc
	v_cmp_lt_u32_e32 vcc, s50, v49
	v_add_u32_e32 v49, 0xfffffe95, v48
	s_nop 0
	v_cndmask_b32_e32 v45, v233, v45, vcc
	v_cmp_lt_u32_e32 vcc, s50, v49
	v_add_u32_e32 v49, 0xfffffeb5, v48
	s_nop 0
	v_cndmask_b32_e32 v78, v233, v78, vcc
	v_cmp_lt_u32_e32 vcc, s50, v49
	v_add_u32_e32 v49, 0xfffffe96, v48
	v_add_u32_e32 v48, 0xfffffeb6, v48
	v_cndmask_b32_e32 v46, v233, v46, vcc
	v_cmp_lt_u32_e32 vcc, s50, v49
	s_nop 1
	v_cndmask_b32_e32 v79, v233, v79, vcc
	v_cmp_lt_u32_e32 vcc, s50, v48
	s_nop 1
	v_cndmask_b32_e32 v47, v233, v47, vcc
.Latt_swa_nomask:
	v_max3_f32 v198, v64, v65, v66
	v_max3_f32 v199, v67, v68, v69
	v_max3_f32 v198, v198, v70, v71
	v_max3_f32 v199, v199, v72, v73
	v_max3_f32 v198, v198, v74, v75
	v_max3_f32 v199, v199, v76, v77
	v_max3_f32 v198, v198, v78, v79
	v_max3_f32 v200, v32, v33, v34
	v_max3_f32 v201, v35, v36, v37
	v_max3_f32 v200, v200, v38, v39
	v_max3_f32 v201, v201, v40, v41
	v_max3_f32 v200, v200, v42, v43
	v_max3_f32 v201, v201, v44, v45
	v_max3_f32 v200, v200, v46, v47
	v_max3_f32 v198, v198, v199, v200
	v_max_f32_e32 v198, v198, v201
	v_mov_b32_e32 v199, v198
	s_nop 1
	v_permlane32_swap_b32_e32 v198, v199
	v_max_f32_e32 v202, v198, v199
	v_cmp_lt_f32_e32 vcc, s58, v202
	s_cbranch_vccz .Latt_swa_norescale
.Latt_swa_rare:
	v_max_f32_e32 v203, 0, v202
	v_max_f32_e32 v204, 0, v203
	v_add_f32_e32 v131, v131, v203
	v_exp_f32_e64 v206, -v204
	v_sub_f32_e32 v154, v154, v203
	v_mov_b32_e32 v155, v154
	v_mov_b32_e32 v156, v154
	v_mov_b32_e32 v157, v154
	v_mov_b32_e32 v158, v154
	v_mov_b32_e32 v159, v154
	v_mov_b32_e32 v160, v154
	v_mov_b32_e32 v161, v154
	v_mov_b32_e32 v162, v154
	v_mov_b32_e32 v163, v154
	v_mov_b32_e32 v164, v154
	v_mov_b32_e32 v165, v154
	v_mov_b32_e32 v166, v154
	v_mov_b32_e32 v167, v154
	v_mov_b32_e32 v168, v154
	v_mov_b32_e32 v169, v154
	v_sub_f32_e32 v64, v64, v203
	v_sub_f32_e32 v65, v65, v203
	v_sub_f32_e32 v66, v66, v203
	v_sub_f32_e32 v67, v67, v203
	v_sub_f32_e32 v68, v68, v203
	v_sub_f32_e32 v69, v69, v203
	v_sub_f32_e32 v70, v70, v203
	v_sub_f32_e32 v71, v71, v203
	v_sub_f32_e32 v72, v72, v203
	v_sub_f32_e32 v73, v73, v203
	v_sub_f32_e32 v74, v74, v203
	v_sub_f32_e32 v75, v75, v203
	v_sub_f32_e32 v76, v76, v203
	v_sub_f32_e32 v77, v77, v203
	v_sub_f32_e32 v78, v78, v203
	v_sub_f32_e32 v79, v79, v203
	v_sub_f32_e32 v32, v32, v203
	v_sub_f32_e32 v33, v33, v203
	v_sub_f32_e32 v34, v34, v203
	v_sub_f32_e32 v35, v35, v203
	v_sub_f32_e32 v36, v36, v203
	v_sub_f32_e32 v37, v37, v203
	v_sub_f32_e32 v38, v38, v203
	v_sub_f32_e32 v39, v39, v203
	v_sub_f32_e32 v40, v40, v203
	v_sub_f32_e32 v41, v41, v203
	v_sub_f32_e32 v42, v42, v203
	v_sub_f32_e32 v43, v43, v203
	v_sub_f32_e32 v44, v44, v203
	v_sub_f32_e32 v45, v45, v203
	v_sub_f32_e32 v46, v46, v203
	v_sub_f32_e32 v47, v47, v203
	v_mul_f32_e32 v121, v121, v206
	v_pk_mul_f32 v[0:1], v[0:1], v[206:207] op_sel_hi:[1,0]
	v_pk_mul_f32 v[2:3], v[2:3], v[206:207] op_sel_hi:[1,0]
	v_pk_mul_f32 v[4:5], v[4:5], v[206:207] op_sel_hi:[1,0]
	v_pk_mul_f32 v[6:7], v[6:7], v[206:207] op_sel_hi:[1,0]
	v_pk_mul_f32 v[8:9], v[8:9], v[206:207] op_sel_hi:[1,0]
	v_pk_mul_f32 v[10:11], v[10:11], v[206:207] op_sel_hi:[1,0]
	v_pk_mul_f32 v[12:13], v[12:13], v[206:207] op_sel_hi:[1,0]
	v_pk_mul_f32 v[14:15], v[14:15], v[206:207] op_sel_hi:[1,0]
	v_pk_mul_f32 v[16:17], v[16:17], v[206:207] op_sel_hi:[1,0]
	v_pk_mul_f32 v[18:19], v[18:19], v[206:207] op_sel_hi:[1,0]
	v_pk_mul_f32 v[20:21], v[20:21], v[206:207] op_sel_hi:[1,0]
	v_pk_mul_f32 v[22:23], v[22:23], v[206:207] op_sel_hi:[1,0]
	v_pk_mul_f32 v[24:25], v[24:25], v[206:207] op_sel_hi:[1,0]
	v_pk_mul_f32 v[26:27], v[26:27], v[206:207] op_sel_hi:[1,0]
	v_pk_mul_f32 v[28:29], v[28:29], v[206:207] op_sel_hi:[1,0]
	v_pk_mul_f32 v[30:31], v[30:31], v[206:207] op_sel_hi:[1,0]
.Latt_swa_norescale:
	v_exp_f32_e32 v64, v64
	v_exp_f32_e32 v65, v65
	v_exp_f32_e32 v66, v66
	v_exp_f32_e32 v67, v67
	v_exp_f32_e32 v68, v68
	v_exp_f32_e32 v69, v69
	v_exp_f32_e32 v70, v70
	v_exp_f32_e32 v71, v71
	v_cvt_pk_bf16_f32 v170, v64, v65
	v_cvt_pk_bf16_f32 v171, v66, v67
	v_cvt_pk_bf16_f32 v172, v68, v69
	v_cvt_pk_bf16_f32 v173, v70, v71
	s_waitcnt lgkmcnt(7)
	s_nop 0
	v_mfma_f32_32x32x16_bf16 v[0:15], v[210:213], v[170:173], v[0:15]
	v_exp_f32_e32 v72, v72
	v_exp_f32_e32 v73, v73
	v_exp_f32_e32 v74, v74
	v_exp_f32_e32 v75, v75
	v_cvt_pk_bf16_f32 v174, v72, v73
	v_exp_f32_e32 v76, v76
	v_exp_f32_e32 v77, v77
	v_cvt_pk_bf16_f32 v175, v74, v75
	s_waitcnt lgkmcnt(6)
	v_mfma_f32_32x32x16_bf16 v[16:31], v[214:217], v[170:173], v[16:31]
	v_exp_f32_e32 v78, v78
	v_exp_f32_e32 v79, v79
	v_cvt_pk_bf16_f32 v176, v76, v77
	v_cvt_pk_bf16_f32 v177, v78, v79
	v_add_f32_e32 v198, v64, v68
	v_add_f32_e32 v199, v65, v69
	v_add_f32_e32 v200, v66, v70
	v_add_f32_e32 v201, v67, v71
	s_waitcnt lgkmcnt(5)
	v_mfma_f32_32x32x16_bf16 v[0:15], v[218:221], v[174:177], v[0:15]
	v_exp_f32_e32 v32, v32
	v_exp_f32_e32 v33, v33
	v_exp_f32_e32 v34, v34
	v_exp_f32_e32 v35, v35
	v_cvt_pk_bf16_f32 v170, v32, v33
	v_exp_f32_e32 v36, v36
	v_exp_f32_e32 v37, v37
	v_cvt_pk_bf16_f32 v171, v34, v35
	v_exp_f32_e32 v38, v38
	v_exp_f32_e32 v39, v39
	s_waitcnt lgkmcnt(4)
	v_mfma_f32_32x32x16_bf16 v[16:31], v[222:225], v[174:177], v[16:31]
	v_cvt_pk_bf16_f32 v172, v36, v37
	v_cvt_pk_bf16_f32 v173, v38, v39
	v_add_f32_e32 v198, v198, v72
	v_add_f32_e32 v199, v199, v73
	v_add_f32_e32 v200, v200, v74
	v_add_f32_e32 v201, v201, v75
	v_add_f32_e32 v198, v198, v76
	v_add_f32_e32 v199, v199, v77
	v_add_f32_e32 v200, v200, v78
	v_add_f32_e32 v201, v201, v79
	s_waitcnt lgkmcnt(3)
	v_mfma_f32_32x32x16_bf16 v[0:15], v[226:229], v[170:173], v[0:15]
	v_exp_f32_e32 v40, v40
	v_exp_f32_e32 v41, v41
	v_exp_f32_e32 v42, v42
	v_exp_f32_e32 v43, v43
	v_cvt_pk_bf16_f32 v174, v40, v41
	v_exp_f32_e32 v44, v44
	v_exp_f32_e32 v45, v45
	v_cvt_pk_bf16_f32 v175, v42, v43
	v_exp_f32_e32 v46, v46
	v_exp_f32_e32 v47, v47
	s_waitcnt lgkmcnt(2)
	v_mfma_f32_32x32x16_bf16 v[16:31], v[238:241], v[170:173], v[16:31]
	v_cvt_pk_bf16_f32 v176, v44, v45
	v_cvt_pk_bf16_f32 v177, v46, v47
	v_add_f32_e32 v198, v198, v32
	v_add_f32_e32 v199, v199, v33
	v_add_f32_e32 v200, v200, v34
	v_add_f32_e32 v201, v201, v35
	v_add_f32_e32 v198, v198, v36
	v_add_f32_e32 v199, v199, v37
	v_add_f32_e32 v200, v200, v38
	v_add_f32_e32 v201, v201, v39
	s_waitcnt lgkmcnt(1)
	v_mfma_f32_32x32x16_bf16 v[0:15], v[242:245], v[174:177], v[0:15]
	v_add_f32_e32 v198, v198, v40
	v_add_f32_e32 v199, v199, v41
	v_add_f32_e32 v200, v200, v42
	v_add_f32_e32 v201, v201, v43
	s_waitcnt lgkmcnt(0)
	v_mfma_f32_32x32x16_bf16 v[16:31], v[246:249], v[174:177], v[16:31]
	v_add_f32_e32 v198, v198, v44
	v_add_f32_e32 v199, v199, v45
	v_add_f32_e32 v200, v200, v46
	v_add_f32_e32 v201, v201, v47
	v_add_f32_e32 v198, v198, v199
	v_add_f32_e32 v200, v200, v201
	v_add_f32_e32 v198, v198, v200
	v_add_f32_e32 v121, v121, v198
.Latt_swa_skip:
	s_and_b64 vcc, exec, s[28:29]
	s_cbranch_vccz .Latt_swa_w_n
	s_waitcnt vmcnt(0)
	s_branch .Latt_swa_w_d
.Latt_swa_w_n:
	s_waitcnt vmcnt(2)
.Latt_swa_w_d:
	s_waitcnt lgkmcnt(0)
	s_barrier
	s_add_i32 s28, s45, 1
	s_cmp_lg_u32 s45, 2
	s_cselect_b32 s28, s28, 0
	s_add_i32 s47, s47, 1
	s_add_i32 s43, s43, 64
	s_cmp_ge_i32 s47, s41
	s_cbranch_scc1 .LBB0_37
	s_mov_b32 s48, s46
	s_mov_b32 s46, s45
	s_mov_b32 s45, s28
	s_branch .LBB0_57

.Latt_diff_skip:
	s_and_b64 vcc, exec, s[46:47]
	s_cbranch_vccz .Latt_diff_w_n
	s_waitcnt vmcnt(0)
	s_branch .Latt_diff_w_d

.Latt_mla_skip:
	s_and_b64 vcc, exec, s[60:61]
	s_cbranch_vccz .Latt_mla_w_n
	s_waitcnt vmcnt(0)
	s_branch .Latt_mla_w_d

.LBB0_211:
	s_and_b64 vcc, exec, s[2:3]
	s_cbranch_vccz .LBB0_367
	v_mov_b32_e32 v0, v191
	v_readlane_b32 s0, v254, 2
	v_readlane_b32 s2, v254, 33
	v_readlane_b32 s1, v254, 3
	s_bitcmp1_b32 s64, 8
	v_mov_b32_e32 v0, s2
	ds_read_b32 v0, v0
	v_readlane_b32 s2, v254, 0
	s_mov_b32 s63, s2
	v_readlane_b32 s2, v254, 47
	v_readlane_b32 s3, v254, 1
	s_waitcnt lgkmcnt(0)
	v_readfirstlane_b32 s62, v0
	v_mov_b32_e32 v0, s2
	ds_read_b32 v0, v0
	s_load_dwordx2 s[2:3], s[0:1], 0xc0
	s_cselect_b32 s0, 0x2c00000, 0
	s_waitcnt lgkmcnt(0)
	s_add_u32 s0, s2, s0
	s_addc_u32 s1, s3, 0
	s_add_u32 s67, s0, 0x400000
	s_addc_u32 s94, s1, 0
	s_add_u32 s12, s2, 0x12800000
	s_addc_u32 s13, s3, 0
	s_add_u32 s14, s2, 0x200000
	s_addc_u32 s15, s3, 0
	v_lshlrev_b32_e32 v249, 4, v191
	global_load_dwordx4 v[250:253], v249, s[14:15]
	v_or_b32_e32 v249, 0x20000, v249
	s_waitcnt vmcnt(0)
	ds_write_b128 v249, v[250:253]
	s_waitcnt lgkmcnt(0)
	s_barrier
	s_and_b32 s0, s65, 0xff
	s_cmp_lg_u32 s0, 0
	s_cbranch_scc0 .LBB0_262
	s_cmp_eq_u32 s0, 1
	s_cselect_b64 s[16:17], -1, 0
	s_and_b64 s[0:1], s[16:17], exec
	s_movk_i32 s0, 0x500
	s_cselect_b32 s0, 0x800, s0
	s_lshr_b32 s74, s0, 8
	s_mul_i32 s96, s74, 0x88
	v_mov_b32_e32 v128, v191
	s_cmp_lt_i32 s62, s96
	s_cselect_b64 s[6:7], -1, 0
	s_cmp_ge_i32 s62, s96
	v_readfirstlane_b32 s20, v128
	s_cbranch_scc1 .LBB0_215
	s_lshr_b32 s8, s0, 5
	s_abs_i32 s9, s8
	v_cvt_f32_u32_e32 v0, s9
	s_ashr_i32 s4, s62, 31
	s_lshr_b32 s4, s4, 29
	s_add_i32 s4, s62, s4
	v_rcp_iflag_f32_e32 v0, v0
	s_and_b32 s5, s4, -8
	s_sub_i32 s5, s62, s5
	s_lshr_b32 s1, s96, 3
	v_mul_f32_e32 v0, 0x4f7ffffe, v0
	v_cvt_u32_f32_e32 v0, v0
	s_lshr_b32 s10, s5, 31
	s_add_i32 s1, s10, s1
	s_sub_i32 s10, 0, s9
	v_readfirstlane_b32 s11, v0
	s_mul_i32 s1, s1, s5
	s_ashr_i32 s4, s4, 3
	s_mul_i32 s10, s10, s11
	s_add_i32 s1, s1, s4
	s_mul_hi_u32 s10, s11, s10
	s_abs_i32 s5, s1
	s_add_i32 s11, s11, s10
	s_mul_hi_u32 s10, s5, s11
	s_mul_i32 s11, s10, s9
	s_xor_b32 s4, s1, s8
	s_sub_i32 s5, s5, s11
	s_ashr_i32 s4, s4, 31
	s_add_i32 s11, s10, 1
	s_sub_i32 s18, s5, s9
	s_cmp_ge_u32 s5, s9
	s_cselect_b32 s10, s11, s10
	s_cselect_b32 s5, s18, s5
	s_add_i32 s11, s10, 1
	s_cmp_ge_u32 s5, s9
	s_cselect_b32 s5, s11, s10
	s_xor_b32 s5, s5, s4
	s_sub_i32 s4, s5, s4
	s_lshl_b32 s9, s4, 3
	s_sub_i32 s5, 0x88, s9
	s_min_i32 s10, s5, 8
	v_cvt_f32_i32_e32 v0, s10
	s_mul_i32 s4, s4, s8
	s_sub_i32 s1, s1, s4
	v_cvt_f32_i32_e32 v1, s1
	v_rcp_iflag_f32_e32 v2, v0
	s_xor_b32 s4, s1, s10
	s_ashr_i32 s4, s4, 30
	s_or_b32 s8, s4, 1
	v_mul_f32_e32 v2, v1, v2
	v_trunc_f32_e32 v2, v2
	v_fma_f32 v1, -v2, v0, v1
	v_cvt_i32_f32_e32 v2, v2
	v_cmp_ge_f32_e64 s[4:5], |v1|, |v0|
	s_and_b64 s[4:5], s[4:5], exec
	s_cselect_b32 s4, s8, 0
	v_readfirstlane_b32 s5, v2
	s_add_i32 s4, s5, s4
	s_sext_i32_i8 s8, s4
	s_mul_i32 s4, s4, s10
	s_sub_i32 s1, s1, s4
	s_sext_i32_i8 s1, s1
	s_add_i32 s10, s9, s1

.LBB0_218:
	s_lshl_b32 s52, s6, 6
	s_lshl_b32 s9, s6, 13
	s_lshl_b32 s6, s7, 5
	s_and_b32 s53, s6, 0x60
	s_add_i32 m0, s40, 0x18000
	v_lshl_add_u64 v[14:15], v[14:15], 0, s[90:91]
	s_lshl_b32 s11, s53, 7
	s_waitcnt vmcnt(2)
	s_barrier
	global_load_lds_dwordx4 v[14:15], off
	v_lshl_add_u64 v[10:11], v[10:11], 0, s[90:91]
	s_add_i32 m0, s40, 0x1a000
	s_add_i32 s55, s40, 0x8000
	s_add_i32 s56, s40, 0xa000
	global_load_lds_dwordx4 v[10:11], off
	v_lshl_add_u64 v[2:3], v[2:3], 0, s[90:91]
	s_mov_b32 m0, s55
	s_add_u32 s6, s44, 0x40080
	global_load_lds_dwordx4 v[2:3], off
	v_lshl_add_u64 v[2:3], v[6:7], 0, s[90:91]
	s_mov_b32 m0, s56
	s_addc_u32 s7, s45, 0
	global_load_lds_dwordx4 v[2:3], off
	s_add_i32 m0, s40, 0x1c000
	v_lshl_add_u64 v[2:3], s[6:7], 0, v[130:131]
	global_load_lds_dwordx4 v[2:3], off
	v_lshl_add_u64 v[2:3], s[6:7], 0, v[132:133]
	s_add_i32 m0, s40, 0x1e000
	s_cmpk_lt_u32 s20, 0x100
	global_load_lds_dwordx4 v[2:3], off
	s_cselect_b64 s[24:25], -1, 0
	s_lshr_b32 s58, s0, 5
	s_abs_i32 s59, s58
	v_cvt_f32_u32_e32 v144, s59
	v_and_b32_e32 v140, 15, v128
	v_bfe_u32 v142, v128, 4, 2
	v_lshlrev_b32_e32 v143, 2, v128
	v_and_b32_e32 v128, 16, v128
	v_cmp_eq_u32_e32 vcc, 0, v128
	v_rcp_iflag_f32_e32 v128, v144
	s_sub_i32 s6, 0, s59
	v_lshlrev_b32_e32 v141, 4, v142
	v_lshlrev_b32_e32 v147, 3, v142
	v_mul_f32_e32 v128, 0x4f7ffffe, v128
	v_cvt_u32_f32_e32 v128, v128
	v_lshl_or_b32 v141, v140, 6, v141
	v_and_b32_e32 v143, 32, v143
	v_lshlrev_b32_e32 v142, 2, v142
	v_readfirstlane_b32 s7, v128
	v_lshlrev_b32_e32 v128, 13, v134
	v_and_b32_e32 v128, 0x7fffc000, v128
	s_mul_i32 s6, s6, s7
	v_lshl_add_u32 v128, v135, 10, v128
	s_mul_hi_u32 s6, s7, s6
	v_or_b32_e32 v128, v128, v145
	s_add_i32 s82, s7, s6
	v_add_lshl_u32 v128, v128, v146, 1
	s_mov_b64 s[6:7], 0x40080
	v_lshl_add_u64 v[134:135], v[128:129], 0, s[6:7]
	v_lshlrev_b32_e32 v128, 13, v136
	v_and_b32_e32 v128, 0x7fffc000, v128
	v_lshl_add_u32 v128, v137, 10, v128
	v_bitop3_b32 v149, v141, s9, v143 bitop3:0xde
	v_bitop3_b32 v141, v141, s11, v143 bitop3:0xde
	s_waitcnt vmcnt(6)
	v_add_u32_e32 v143, 12, v142
	v_or_b32_e32 v128, v128, v138
	v_cndmask_b32_e32 v148, v143, v142, vcc
	v_add_lshl_u32 v128, v128, v139, 1
	v_mov_b32_e32 v125, v124
	v_mov_b32_e32 v126, v124
	v_mov_b32_e32 v127, v124
	v_mov_b32_e32 v121, v120
	v_mov_b32_e32 v122, v120
	v_mov_b32_e32 v123, v120
	v_mov_b32_e32 v117, v116
	v_mov_b32_e32 v118, v116
	v_mov_b32_e32 v119, v116
	v_mov_b32_e32 v113, v112
	v_mov_b32_e32 v114, v112
	v_mov_b32_e32 v115, v112
	v_mov_b32_e32 v109, v108
	v_mov_b32_e32 v110, v108
	v_mov_b32_e32 v111, v108
	v_mov_b32_e32 v105, v104
	v_mov_b32_e32 v106, v104
	v_mov_b32_e32 v107, v104
	v_mov_b32_e32 v101, v100
	v_mov_b32_e32 v102, v100
	v_mov_b32_e32 v103, v100
	v_mov_b32_e32 v97, v96
	v_mov_b32_e32 v98, v96
	v_mov_b32_e32 v99, v96
	v_mov_b32_e32 v61, v60
	v_mov_b32_e32 v62, v60
	v_mov_b32_e32 v63, v60
	v_mov_b32_e32 v57, v56
	v_mov_b32_e32 v58, v56
	v_mov_b32_e32 v59, v56
	v_mov_b32_e32 v53, v52
	v_mov_b32_e32 v54, v52
	v_mov_b32_e32 v55, v52
	v_mov_b32_e32 v49, v48
	v_mov_b32_e32 v50, v48
	v_mov_b32_e32 v51, v48
	v_mov_b32_e32 v45, v44
	v_mov_b32_e32 v46, v44
	v_mov_b32_e32 v47, v44
	v_mov_b32_e32 v41, v40
	v_mov_b32_e32 v42, v40
	v_mov_b32_e32 v43, v40
	v_mov_b32_e32 v37, v36
	v_mov_b32_e32 v38, v36
	v_mov_b32_e32 v39, v36
	v_mov_b32_e32 v33, v32
	v_mov_b32_e32 v34, v32
	v_mov_b32_e32 v35, v32
	v_mov_b32_e32 v93, v92
	v_mov_b32_e32 v94, v92
	v_mov_b32_e32 v95, v92
	v_mov_b32_e32 v89, v88
	v_mov_b32_e32 v90, v88
	v_mov_b32_e32 v91, v88
	v_mov_b32_e32 v85, v84
	v_mov_b32_e32 v86, v84
	v_mov_b32_e32 v87, v84
	v_mov_b32_e32 v81, v80
	v_mov_b32_e32 v82, v80
	v_mov_b32_e32 v83, v80
	v_mov_b32_e32 v77, v76
	v_mov_b32_e32 v78, v76
	v_mov_b32_e32 v79, v76
	v_mov_b32_e32 v73, v72
	v_mov_b32_e32 v74, v72
	v_mov_b32_e32 v75, v72
	v_mov_b32_e32 v69, v68
	v_mov_b32_e32 v70, v68
	v_mov_b32_e32 v71, v68
	v_mov_b32_e32 v65, v64
	v_mov_b32_e32 v66, v64
	v_mov_b32_e32 v67, v64
	v_mov_b32_e32 v29, v28
	v_mov_b32_e32 v30, v28
	v_mov_b32_e32 v31, v28
	v_mov_b32_e32 v25, v24
	v_mov_b32_e32 v26, v24
	v_mov_b32_e32 v27, v24
	v_mov_b32_e32 v21, v20
	v_mov_b32_e32 v22, v20
	v_mov_b32_e32 v23, v20
	v_mov_b32_e32 v17, v16
	v_mov_b32_e32 v18, v16
	v_mov_b32_e32 v19, v16
	v_mov_b32_e32 v13, v12
	v_mov_b32_e32 v14, v12
	v_mov_b32_e32 v15, v12
	v_mov_b32_e32 v9, v8
	v_mov_b32_e32 v10, v8
	v_mov_b32_e32 v11, v8
	v_mov_b32_e32 v5, v4
	v_mov_b32_e32 v6, v4
	v_mov_b32_e32 v7, v4
	v_mov_b32_e32 v1, v0
	v_mov_b32_e32 v2, v0
	v_mov_b32_e32 v3, v0
	s_mov_b32 s57, 0
	v_or_b32_e32 v142, 16, v140
	v_or_b32_e32 v143, 32, v140
	v_or_b32_e32 v144, 48, v140
	s_ashr_i32 s60, s63, 31
	s_ashr_i32 s61, s62, 31
	s_mul_i32 s74, s74, 17
	s_ashr_i32 s81, s58, 31
	v_lshl_add_u64 v[136:137], v[128:129], 0, s[6:7]
	v_add_u32_e32 v145, 0, v149
	v_lshlrev_b32_e32 v128, 1, v148
	v_lshlrev_b32_e32 v146, 2, v147
	v_or_b32_e32 v146, 0x20000, v146
	s_barrier
	s_branch .LBB0_221

.LBB0_227:
	s_cmpk_lt_i32 s10, 0x80
	s_cselect_b64 s[30:31], -1, 0
	s_lshl_b32 s9, s8, 8
	s_bfe_i32 s8, s8, 0x10017
	s_or_b32 s38, s9, s53
	s_lshr_b32 s8, s8, 26
	s_add_i32 s8, s38, s8
	s_lshl_b32 s21, s10, 8
	s_andn2_b32 s8, s8, 63
	s_add_i32 s21, s21, s52
	s_sub_i32 s10, s38, s8
	s_cmp_gt_i32 s10, -1
	s_cselect_b64 s[8:9], -1, 0
	s_and_b64 s[30:31], s[30:31], s[8:9]
	s_bitcmp0_b32 s10, 5
	v_cndmask_b32_e64 v138, 0, 1, s[30:31]
	s_cselect_b64 s[8:9], -1, 0
	v_cmp_ne_u32_e64 s[10:11], 1, v138
	s_andn2_b64 vcc, exec, s[30:31]
	s_bfe_u32 s20, s21, 0x60006
	s_cbranch_vccnz .LBB0_229
	v_mov_b32_e32 v138, s20
	v_cndmask_b32_e64 v138, v140, v138, s[8:9]
	v_lshl_or_b32 v138, v138, 7, v146
	ds_read_b128 v[148:151], v138
	ds_read_b128 v[152:155], v138 offset:16
	s_waitcnt lgkmcnt(0)
	v_mov_b32_e32 v138, v149
	v_mov_b32_e32 v139, v151
	v_mov_b32_e32 v156, v153
	v_mov_b32_e32 v157, v155
	v_mov_b32_e32 v153, v154
	v_mov_b32_e32 v149, v150
	v_pk_mul_f32 v[150:151], v[120:121], v[138:139]
	v_pk_mul_f32 v[154:155], v[122:123], v[156:157]
	v_pk_mul_f32 v[138:139], v[124:125], v[138:139]
	v_pk_mul_f32 v[156:157], v[126:127], v[156:157]
	v_pk_fma_f32 v[126:127], v[126:127], v[152:153], v[154:155] neg_lo:[0,0,1] neg_hi:[0,0,1]
	v_pk_fma_f32 v[124:125], v[124:125], v[148:149], v[150:151] neg_lo:[0,0,1] neg_hi:[0,0,1]
	v_pk_fma_f32 v[122:123], v[122:123], v[152:153], v[156:157]
	v_pk_fma_f32 v[120:121], v[120:121], v[148:149], v[138:139]
.LBB0_229:
	s_cmpk_lt_i32 s38, 0x400
	s_cselect_b64 vcc, -1, 0
	v_cndmask_b32_e32 v138, 1.0, v234, vcc
	v_or_b32_e32 v139, s21, v140
	v_pk_mul_f32 v[124:125], v[138:139], v[124:125] op_sel_hi:[0,1]
	v_pk_mul_f32 v[120:121], v[138:139], v[120:121] op_sel_hi:[0,1]
	v_pk_mul_f32 v[148:149], v[138:139], v[122:123] op_sel_hi:[0,1]
	v_cvt_pk_bf16_f32 v122, v124, v125
	v_cvt_pk_bf16_f32 v124, v120, v121
	v_mad_i64_i32 v[120:121], s[30:31], v139, s0, 0
	s_ashr_i32 s39, s38, 31
	v_pk_mul_f32 v[126:127], v[138:139], v[126:127] op_sel_hi:[0,1]
	v_lshl_add_u64 v[120:121], v[120:121], 1, s[12:13]
	v_cvt_pk_bf16_f32 v123, v126, v127
	v_cvt_pk_bf16_f32 v125, v148, v149
	v_lshl_add_u64 v[120:121], s[38:39], 1, v[120:121]
	v_permlane16_swap_b32_e32 v122, v124
	v_permlane16_swap_b32_e32 v123, v125
	v_lshl_add_u64 v[120:121], v[120:121], 0, v[128:129]
	global_store_dwordx4 v[120:121], v[122:125], off
	s_and_b64 vcc, exec, s[10:11]
	s_cbranch_vccnz .LBB0_231
	v_mov_b32_e32 v122, s20
	v_cndmask_b32_e64 v122, v142, v122, s[8:9]
	v_lshl_or_b32 v126, v122, 7, v146
	ds_read_b128 v[122:125], v126
	ds_read_b128 v[148:151], v126 offset:16
	s_waitcnt lgkmcnt(0)
	v_mov_b32_e32 v126, v123
	v_mov_b32_e32 v127, v125
	v_mov_b32_e32 v152, v149
	v_mov_b32_e32 v153, v151
	v_mov_b32_e32 v149, v150
	v_mov_b32_e32 v123, v124
	v_pk_mul_f32 v[124:125], v[112:113], v[126:127]
	v_pk_mul_f32 v[150:151], v[114:115], v[152:153]
	v_pk_mul_f32 v[126:127], v[116:117], v[126:127]
	v_pk_mul_f32 v[152:153], v[118:119], v[152:153]
	v_pk_fma_f32 v[118:119], v[118:119], v[148:149], v[150:151] neg_lo:[0,0,1] neg_hi:[0,0,1]
	v_pk_fma_f32 v[116:117], v[116:117], v[122:123], v[124:125] neg_lo:[0,0,1] neg_hi:[0,0,1]
	v_pk_fma_f32 v[114:115], v[114:115], v[148:149], v[152:153]
	v_pk_fma_f32 v[112:113], v[112:113], v[122:123], v[126:127]
.LBB0_231:
	v_mov_b32_e32 v139, v138
	v_or_b32_e32 v126, s21, v142
	v_mov_b32_e32 v122, v138
	v_mov_b32_e32 v123, v138
	v_pk_mul_f32 v[116:117], v[138:139], v[116:117]
	v_pk_mul_f32 v[112:113], v[138:139], v[112:113]
	v_pk_mul_f32 v[124:125], v[122:123], v[114:115]
	v_cvt_pk_bf16_f32 v114, v116, v117
	v_cvt_pk_bf16_f32 v116, v112, v113
	v_mad_i64_i32 v[112:113], s[30:31], v126, s0, 0
	v_pk_mul_f32 v[118:119], v[122:123], v[118:119]
	v_lshl_add_u64 v[112:113], v[112:113], 1, s[12:13]
	v_cvt_pk_bf16_f32 v115, v118, v119
	v_cvt_pk_bf16_f32 v117, v124, v125
	v_lshl_add_u64 v[112:113], s[38:39], 1, v[112:113]
	v_permlane16_swap_b32_e32 v114, v116
	v_permlane16_swap_b32_e32 v115, v117
	v_lshl_add_u64 v[112:113], v[112:113], 0, v[128:129]
	global_store_dwordx4 v[112:113], v[114:117], off
	s_and_b64 vcc, exec, s[10:11]
	s_cbranch_vccnz .LBB0_233
	v_mov_b32_e32 v114, s20
	v_cndmask_b32_e64 v114, v143, v114, s[8:9]
	v_lshl_or_b32 v118, v114, 7, v146
	ds_read_b128 v[114:117], v118
	ds_read_b128 v[124:127], v118 offset:16
	s_waitcnt lgkmcnt(0)
	v_mov_b32_e32 v118, v115
	v_mov_b32_e32 v119, v117
	v_mov_b32_e32 v148, v125
	v_mov_b32_e32 v149, v127
	v_mov_b32_e32 v125, v126
	v_mov_b32_e32 v115, v116
	v_pk_mul_f32 v[116:117], v[104:105], v[118:119]
	v_pk_mul_f32 v[126:127], v[106:107], v[148:149]
	v_pk_mul_f32 v[118:119], v[108:109], v[118:119]
	v_pk_mul_f32 v[148:149], v[110:111], v[148:149]
	v_pk_fma_f32 v[110:111], v[110:111], v[124:125], v[126:127] neg_lo:[0,0,1] neg_hi:[0,0,1]
	v_pk_fma_f32 v[108:109], v[108:109], v[114:115], v[116:117] neg_lo:[0,0,1] neg_hi:[0,0,1]
	v_pk_fma_f32 v[106:107], v[106:107], v[124:125], v[148:149]
	v_pk_fma_f32 v[104:105], v[104:105], v[114:115], v[118:119]
.LBB0_233:
	v_or_b32_e32 v116, s21, v143
	v_pk_mul_f32 v[108:109], v[138:139], v[108:109]
	v_pk_mul_f32 v[104:105], v[138:139], v[104:105]
	v_pk_mul_f32 v[114:115], v[122:123], v[106:107]
	v_cvt_pk_bf16_f32 v106, v108, v109
	v_cvt_pk_bf16_f32 v108, v104, v105
	v_mad_i64_i32 v[104:105], s[30:31], v116, s0, 0
	v_pk_mul_f32 v[110:111], v[122:123], v[110:111]
	v_lshl_add_u64 v[104:105], v[104:105], 1, s[12:13]
	v_cvt_pk_bf16_f32 v107, v110, v111
	v_cvt_pk_bf16_f32 v109, v114, v115
	v_lshl_add_u64 v[104:105], s[38:39], 1, v[104:105]
	v_permlane16_swap_b32_e32 v106, v108
	v_permlane16_swap_b32_e32 v107, v109
	v_lshl_add_u64 v[104:105], v[104:105], 0, v[128:129]
	global_store_dwordx4 v[104:105], v[106:109], off
	s_and_b64 vcc, exec, s[10:11]
	s_cbranch_vccnz .LBB0_235
	v_mov_b32_e32 v106, s20
	v_cndmask_b32_e64 v106, v144, v106, s[8:9]
	v_lshl_or_b32 v110, v106, 7, v146
	ds_read_b128 v[106:109], v110
	ds_read_b128 v[114:117], v110 offset:16
	s_waitcnt lgkmcnt(0)
	v_mov_b32_e32 v110, v107
	v_mov_b32_e32 v111, v109
	v_mov_b32_e32 v118, v115
	v_mov_b32_e32 v119, v117
	v_mov_b32_e32 v115, v116
	v_mov_b32_e32 v107, v108
	v_pk_mul_f32 v[108:109], v[96:97], v[110:111]
	v_pk_mul_f32 v[116:117], v[98:99], v[118:119]
	v_pk_mul_f32 v[110:111], v[100:101], v[110:111]
	v_pk_mul_f32 v[118:119], v[102:103], v[118:119]
	v_pk_fma_f32 v[102:103], v[102:103], v[114:115], v[116:117] neg_lo:[0,0,1] neg_hi:[0,0,1]
	v_pk_fma_f32 v[100:101], v[100:101], v[106:107], v[108:109] neg_lo:[0,0,1] neg_hi:[0,0,1]
	v_pk_fma_f32 v[98:99], v[98:99], v[114:115], v[118:119]
	v_pk_fma_f32 v[96:97], v[96:97], v[106:107], v[110:111]
.LBB0_235:
	v_or_b32_e32 v110, s21, v144
	v_mov_b32_e32 v106, v138
	v_mov_b32_e32 v107, v138
	v_pk_mul_f32 v[100:101], v[138:139], v[100:101]
	v_pk_mul_f32 v[96:97], v[138:139], v[96:97]
	v_pk_mul_f32 v[108:109], v[106:107], v[98:99]
	v_cvt_pk_bf16_f32 v98, v100, v101
	v_cvt_pk_bf16_f32 v100, v96, v97
	v_mad_i64_i32 v[96:97], s[30:31], v110, s0, 0
	v_pk_mul_f32 v[102:103], v[106:107], v[102:103]
	v_lshl_add_u64 v[96:97], v[96:97], 1, s[12:13]
	v_cvt_pk_bf16_f32 v99, v102, v103
	v_cvt_pk_bf16_f32 v101, v108, v109
	v_lshl_add_u64 v[96:97], s[38:39], 1, v[96:97]
	v_permlane16_swap_b32_e32 v98, v100
	v_permlane16_swap_b32_e32 v99, v101
	v_lshl_add_u64 v[96:97], v[96:97], 0, v[128:129]
	global_store_dwordx4 v[96:97], v[98:101], off
	s_add_i32 s27, s21, 0x80
	s_and_b64 vcc, exec, s[10:11]
	s_bfe_u32 s21, s27, 0x60006
	s_cbranch_vccnz .LBB0_237
	v_mov_b32_e32 v98, s21
	v_cndmask_b32_e64 v98, v140, v98, s[8:9]
	v_lshl_or_b32 v102, v98, 7, v146
	ds_read_b128 v[98:101], v102
	ds_read_b128 v[108:111], v102 offset:16
	s_waitcnt lgkmcnt(0)
	v_mov_b32_e32 v102, v99
	v_mov_b32_e32 v103, v101
	v_mov_b32_e32 v114, v109
	v_mov_b32_e32 v115, v111
	v_mov_b32_e32 v109, v110
	v_mov_b32_e32 v99, v100
	v_pk_mul_f32 v[100:101], v[88:89], v[102:103]
	v_pk_mul_f32 v[110:111], v[90:91], v[114:115]
	v_pk_mul_f32 v[102:103], v[92:93], v[102:103]
	v_pk_mul_f32 v[114:115], v[94:95], v[114:115]
	v_pk_fma_f32 v[94:95], v[94:95], v[108:109], v[110:111] neg_lo:[0,0,1] neg_hi:[0,0,1]
	v_pk_fma_f32 v[92:93], v[92:93], v[98:99], v[100:101] neg_lo:[0,0,1] neg_hi:[0,0,1]
	v_pk_fma_f32 v[90:91], v[90:91], v[108:109], v[114:115]
	v_pk_fma_f32 v[88:89], v[88:89], v[98:99], v[102:103]
.LBB0_237:
	v_or_b32_e32 v100, s27, v140
	v_pk_mul_f32 v[92:93], v[138:139], v[92:93]
	v_pk_mul_f32 v[88:89], v[138:139], v[88:89]
	v_pk_mul_f32 v[98:99], v[106:107], v[90:91]
	v_cvt_pk_bf16_f32 v90, v92, v93
	v_cvt_pk_bf16_f32 v92, v88, v89
	v_mad_i64_i32 v[88:89], s[30:31], v100, s0, 0
	v_pk_mul_f32 v[94:95], v[106:107], v[94:95]
	v_lshl_add_u64 v[88:89], v[88:89], 1, s[12:13]
	v_cvt_pk_bf16_f32 v91, v94, v95
	v_cvt_pk_bf16_f32 v93, v98, v99
	v_lshl_add_u64 v[88:89], s[38:39], 1, v[88:89]
	v_permlane16_swap_b32_e32 v90, v92
	v_permlane16_swap_b32_e32 v91, v93
	v_lshl_add_u64 v[88:89], v[88:89], 0, v[128:129]
	global_store_dwordx4 v[88:89], v[90:93], off
	s_and_b64 vcc, exec, s[10:11]
	s_cbranch_vccnz .LBB0_239
	v_mov_b32_e32 v90, s21
	v_cndmask_b32_e64 v90, v142, v90, s[8:9]
	v_lshl_or_b32 v94, v90, 7, v146
	ds_read_b128 v[90:93], v94
	ds_read_b128 v[98:101], v94 offset:16
	s_waitcnt lgkmcnt(0)
	v_mov_b32_e32 v94, v91
	v_mov_b32_e32 v95, v93
	v_mov_b32_e32 v102, v99
	v_mov_b32_e32 v103, v101
	v_mov_b32_e32 v99, v100
	v_mov_b32_e32 v91, v92
	v_pk_mul_f32 v[92:93], v[80:81], v[94:95]
	v_pk_mul_f32 v[100:101], v[82:83], v[102:103]
	v_pk_mul_f32 v[94:95], v[84:85], v[94:95]
	v_pk_mul_f32 v[102:103], v[86:87], v[102:103]
	v_pk_fma_f32 v[86:87], v[86:87], v[98:99], v[100:101] neg_lo:[0,0,1] neg_hi:[0,0,1]
	v_pk_fma_f32 v[84:85], v[84:85], v[90:91], v[92:93] neg_lo:[0,0,1] neg_hi:[0,0,1]
	v_pk_fma_f32 v[82:83], v[82:83], v[98:99], v[102:103]
	v_pk_fma_f32 v[80:81], v[80:81], v[90:91], v[94:95]
.LBB0_239:
	v_or_b32_e32 v94, s27, v142
	v_mov_b32_e32 v90, v138
	v_mov_b32_e32 v91, v138
	v_pk_mul_f32 v[84:85], v[138:139], v[84:85]
	v_pk_mul_f32 v[80:81], v[138:139], v[80:81]
	v_pk_mul_f32 v[92:93], v[90:91], v[82:83]
	v_cvt_pk_bf16_f32 v82, v84, v85
	v_cvt_pk_bf16_f32 v84, v80, v81
	v_mad_i64_i32 v[80:81], s[30:31], v94, s0, 0
	v_pk_mul_f32 v[86:87], v[90:91], v[86:87]
	v_lshl_add_u64 v[80:81], v[80:81], 1, s[12:13]
	v_cvt_pk_bf16_f32 v83, v86, v87
	v_cvt_pk_bf16_f32 v85, v92, v93
	v_lshl_add_u64 v[80:81], s[38:39], 1, v[80:81]
	v_permlane16_swap_b32_e32 v82, v84
	v_permlane16_swap_b32_e32 v83, v85
	v_lshl_add_u64 v[80:81], v[80:81], 0, v[128:129]
	global_store_dwordx4 v[80:81], v[82:85], off
	s_and_b64 vcc, exec, s[10:11]
	s_cbranch_vccnz .LBB0_241
	v_mov_b32_e32 v82, s21
	v_cndmask_b32_e64 v82, v143, v82, s[8:9]
	v_lshl_or_b32 v86, v82, 7, v146
	ds_read_b128 v[82:85], v86
	ds_read_b128 v[92:95], v86 offset:16
	s_waitcnt lgkmcnt(0)
	v_mov_b32_e32 v86, v83
	v_mov_b32_e32 v87, v85
	v_mov_b32_e32 v98, v93
	v_mov_b32_e32 v99, v95
	v_mov_b32_e32 v93, v94
	v_mov_b32_e32 v83, v84
	v_pk_mul_f32 v[84:85], v[72:73], v[86:87]
	v_pk_mul_f32 v[94:95], v[74:75], v[98:99]
	v_pk_mul_f32 v[86:87], v[76:77], v[86:87]
	v_pk_mul_f32 v[98:99], v[78:79], v[98:99]
	v_pk_fma_f32 v[78:79], v[78:79], v[92:93], v[94:95] neg_lo:[0,0,1] neg_hi:[0,0,1]
	v_pk_fma_f32 v[76:77], v[76:77], v[82:83], v[84:85] neg_lo:[0,0,1] neg_hi:[0,0,1]
	v_pk_fma_f32 v[74:75], v[74:75], v[92:93], v[98:99]
	v_pk_fma_f32 v[72:73], v[72:73], v[82:83], v[86:87]
.LBB0_241:
	v_or_b32_e32 v84, s27, v143
	v_pk_mul_f32 v[76:77], v[138:139], v[76:77]
	v_pk_mul_f32 v[72:73], v[138:139], v[72:73]
	v_pk_mul_f32 v[82:83], v[90:91], v[74:75]
	v_cvt_pk_bf16_f32 v74, v76, v77
	v_cvt_pk_bf16_f32 v76, v72, v73
	v_mad_i64_i32 v[72:73], s[30:31], v84, s0, 0
	v_pk_mul_f32 v[78:79], v[90:91], v[78:79]
	v_lshl_add_u64 v[72:73], v[72:73], 1, s[12:13]
	v_cvt_pk_bf16_f32 v75, v78, v79
	v_cvt_pk_bf16_f32 v77, v82, v83
	v_lshl_add_u64 v[72:73], s[38:39], 1, v[72:73]
	v_permlane16_swap_b32_e32 v74, v76
	v_permlane16_swap_b32_e32 v75, v77
	v_lshl_add_u64 v[72:73], v[72:73], 0, v[128:129]
	global_store_dwordx4 v[72:73], v[74:77], off
	s_and_b64 vcc, exec, s[10:11]
	s_cbranch_vccnz .LBB0_243
	v_mov_b32_e32 v74, s21
	v_cndmask_b32_e64 v74, v144, v74, s[8:9]
	v_lshl_or_b32 v78, v74, 7, v146
	ds_read_b128 v[74:77], v78
	ds_read_b128 v[82:85], v78 offset:16
	s_waitcnt lgkmcnt(0)
	v_mov_b32_e32 v78, v75
	v_mov_b32_e32 v79, v77
	v_mov_b32_e32 v86, v83
	v_mov_b32_e32 v87, v85
	v_mov_b32_e32 v83, v84
	v_mov_b32_e32 v75, v76
	v_pk_mul_f32 v[76:77], v[64:65], v[78:79]
	v_pk_mul_f32 v[84:85], v[66:67], v[86:87]
	v_pk_mul_f32 v[78:79], v[68:69], v[78:79]
	v_pk_mul_f32 v[86:87], v[70:71], v[86:87]
	v_pk_fma_f32 v[70:71], v[70:71], v[82:83], v[84:85] neg_lo:[0,0,1] neg_hi:[0,0,1]
	v_pk_fma_f32 v[68:69], v[68:69], v[74:75], v[76:77] neg_lo:[0,0,1] neg_hi:[0,0,1]
	v_pk_fma_f32 v[66:67], v[66:67], v[82:83], v[86:87]
	v_pk_fma_f32 v[64:65], v[64:65], v[74:75], v[78:79]
.LBB0_243:
	v_or_b32_e32 v76, s27, v144
	v_mov_b32_e32 v74, v138
	v_mov_b32_e32 v75, v138
	v_pk_mul_f32 v[68:69], v[138:139], v[68:69]
	v_pk_mul_f32 v[64:65], v[138:139], v[64:65]
	v_pk_mul_f32 v[70:71], v[74:75], v[70:71]
	v_pk_mul_f32 v[74:75], v[74:75], v[66:67]
	v_cvt_pk_bf16_f32 v66, v68, v69
	v_cvt_pk_bf16_f32 v68, v64, v65
	v_mad_i64_i32 v[64:65], s[30:31], v76, s0, 0
	v_lshl_add_u64 v[64:65], v[64:65], 1, s[12:13]
	v_cvt_pk_bf16_f32 v67, v70, v71
	v_cvt_pk_bf16_f32 v69, v74, v75
	v_lshl_add_u64 v[64:65], s[38:39], 1, v[64:65]
	v_permlane16_swap_b32_e32 v66, v68
	v_permlane16_swap_b32_e32 v67, v69
	v_lshl_add_u64 v[64:65], v[64:65], 0, v[128:129]
	global_store_dwordx4 v[64:65], v[66:69], off
	s_and_b64 vcc, exec, s[10:11]
	s_cbranch_vccnz .LBB0_245
	v_mov_b32_e32 v66, s20
	v_cndmask_b32_e64 v66, v140, v66, s[8:9]
	v_lshl_or_b32 v70, v66, 7, v146
	ds_read_b128 v[66:69], v70
	ds_read_b128 v[74:77], v70 offset:16
	s_waitcnt lgkmcnt(0)
	v_mov_b32_e32 v70, v67
	v_mov_b32_e32 v71, v69
	v_mov_b32_e32 v78, v75
	v_mov_b32_e32 v79, v77
	v_mov_b32_e32 v75, v76
	v_mov_b32_e32 v67, v68
	v_pk_mul_f32 v[68:69], v[56:57], v[70:71]
	v_pk_mul_f32 v[76:77], v[58:59], v[78:79]
	v_pk_mul_f32 v[70:71], v[60:61], v[70:71]
	v_pk_mul_f32 v[78:79], v[62:63], v[78:79]
	v_pk_fma_f32 v[62:63], v[62:63], v[74:75], v[76:77] neg_lo:[0,0,1] neg_hi:[0,0,1]
	v_pk_fma_f32 v[60:61], v[60:61], v[66:67], v[68:69] neg_lo:[0,0,1] neg_hi:[0,0,1]
	v_pk_fma_f32 v[58:59], v[58:59], v[74:75], v[78:79]
	v_pk_fma_f32 v[56:57], v[56:57], v[66:67], v[70:71]
.LBB0_245:
	s_or_b32 s27, s38, 0x80
	s_cmpk_lt_i32 s27, 0x400
	s_cselect_b64 vcc, -1, 0
	v_cndmask_b32_e32 v66, 1.0, v234, vcc
	v_pk_mul_f32 v[62:63], v[66:67], v[62:63] op_sel_hi:[0,1]
	v_pk_mul_f32 v[60:61], v[66:67], v[60:61] op_sel_hi:[0,1]
	v_pk_mul_f32 v[68:69], v[66:67], v[58:59] op_sel_hi:[0,1]
	v_pk_mul_f32 v[58:59], v[66:67], v[56:57] op_sel_hi:[0,1]
	v_cvt_pk_bf16_f32 v56, v60, v61
	v_cvt_pk_bf16_f32 v57, v62, v63
	v_cvt_pk_bf16_f32 v58, v58, v59
	v_cvt_pk_bf16_f32 v59, v68, v69
	s_nop 0
	v_permlane16_swap_b32_e32 v56, v58
	v_permlane16_swap_b32_e32 v57, v59
	global_store_dwordx4 v[120:121], v[56:59], off offset:256
	s_and_b64 vcc, exec, s[10:11]
	s_cbranch_vccnz .LBB0_247
	v_mov_b32_e32 v56, s20
	v_cndmask_b32_e64 v56, v142, v56, s[8:9]
	v_lshl_or_b32 v60, v56, 7, v146
	ds_read_b128 v[56:59], v60
	s_nop 0
	ds_read_b128 v[60:63], v60 offset:16
	s_waitcnt lgkmcnt(0)
	v_mov_b32_e32 v68, v57
	v_mov_b32_e32 v69, v59
	v_mov_b32_e32 v70, v61
	v_mov_b32_e32 v71, v63
	v_mov_b32_e32 v61, v62
	v_mov_b32_e32 v57, v58
	v_pk_mul_f32 v[58:59], v[48:49], v[68:69]
	v_pk_mul_f32 v[62:63], v[50:51], v[70:71]
	v_pk_mul_f32 v[68:69], v[52:53], v[68:69]
	v_pk_mul_f32 v[70:71], v[54:55], v[70:71]
	v_pk_fma_f32 v[54:55], v[54:55], v[60:61], v[62:63] neg_lo:[0,0,1] neg_hi:[0,0,1]
	v_pk_fma_f32 v[52:53], v[52:53], v[56:57], v[58:59] neg_lo:[0,0,1] neg_hi:[0,0,1]
	v_pk_fma_f32 v[50:51], v[50:51], v[60:61], v[70:71]
	v_pk_fma_f32 v[48:49], v[48:49], v[56:57], v[68:69]
.LBB0_247:
	v_mov_b32_e32 v67, v66
	v_mov_b32_e32 v56, v66
	v_mov_b32_e32 v57, v66
	v_pk_mul_f32 v[54:55], v[56:57], v[54:55]
	v_pk_mul_f32 v[52:53], v[66:67], v[52:53]
	v_pk_mul_f32 v[58:59], v[56:57], v[50:51]
	v_pk_mul_f32 v[50:51], v[66:67], v[48:49]
	v_cvt_pk_bf16_f32 v48, v52, v53
	v_cvt_pk_bf16_f32 v49, v54, v55
	v_cvt_pk_bf16_f32 v50, v50, v51
	v_cvt_pk_bf16_f32 v51, v58, v59
	s_nop 0
	v_permlane16_swap_b32_e32 v48, v50
	v_permlane16_swap_b32_e32 v49, v51
	global_store_dwordx4 v[112:113], v[48:51], off offset:256
	s_and_b64 vcc, exec, s[10:11]
	s_cbranch_vccnz .LBB0_249
	v_mov_b32_e32 v48, s20
	v_cndmask_b32_e64 v48, v143, v48, s[8:9]
	v_lshl_or_b32 v52, v48, 7, v146
	ds_read_b128 v[48:51], v52
	s_nop 0
	ds_read_b128 v[52:55], v52 offset:16
	s_waitcnt lgkmcnt(0)
	v_mov_b32_e32 v58, v49
	v_mov_b32_e32 v59, v51
	v_mov_b32_e32 v60, v53
	v_mov_b32_e32 v61, v55
	v_mov_b32_e32 v53, v54
	v_mov_b32_e32 v49, v50
	v_pk_mul_f32 v[50:51], v[40:41], v[58:59]
	v_pk_mul_f32 v[54:55], v[42:43], v[60:61]
	v_pk_mul_f32 v[58:59], v[44:45], v[58:59]
	v_pk_mul_f32 v[60:61], v[46:47], v[60:61]
	v_pk_fma_f32 v[46:47], v[46:47], v[52:53], v[54:55] neg_lo:[0,0,1] neg_hi:[0,0,1]
	v_pk_fma_f32 v[44:45], v[44:45], v[48:49], v[50:51] neg_lo:[0,0,1] neg_hi:[0,0,1]
	v_pk_fma_f32 v[42:43], v[42:43], v[52:53], v[60:61]
	v_pk_fma_f32 v[40:41], v[40:41], v[48:49], v[58:59]
.LBB0_249:
	v_pk_mul_f32 v[46:47], v[56:57], v[46:47]
	v_pk_mul_f32 v[44:45], v[66:67], v[44:45]
	v_pk_mul_f32 v[48:49], v[56:57], v[42:43]
	v_pk_mul_f32 v[42:43], v[66:67], v[40:41]
	v_cvt_pk_bf16_f32 v40, v44, v45
	v_cvt_pk_bf16_f32 v41, v46, v47
	v_cvt_pk_bf16_f32 v42, v42, v43
	v_cvt_pk_bf16_f32 v43, v48, v49
	s_nop 0
	v_permlane16_swap_b32_e32 v40, v42
	v_permlane16_swap_b32_e32 v41, v43
	global_store_dwordx4 v[104:105], v[40:43], off offset:256
	s_and_b64 vcc, exec, s[10:11]
	s_cbranch_vccnz .LBB0_251
	v_mov_b32_e32 v40, s20
	v_cndmask_b32_e64 v40, v144, v40, s[8:9]
	v_lshl_or_b32 v44, v40, 7, v146
	ds_read_b128 v[40:43], v44
	s_nop 0
	ds_read_b128 v[44:47], v44 offset:16
	s_waitcnt lgkmcnt(0)
	v_mov_b32_e32 v48, v41
	v_mov_b32_e32 v49, v43
	v_mov_b32_e32 v50, v45
	v_mov_b32_e32 v51, v47
	v_mov_b32_e32 v45, v46
	v_mov_b32_e32 v41, v42
	v_pk_mul_f32 v[42:43], v[32:33], v[48:49]
	v_pk_mul_f32 v[46:47], v[34:35], v[50:51]
	v_pk_mul_f32 v[48:49], v[36:37], v[48:49]
	v_pk_mul_f32 v[50:51], v[38:39], v[50:51]
	v_pk_fma_f32 v[38:39], v[38:39], v[44:45], v[46:47] neg_lo:[0,0,1] neg_hi:[0,0,1]
	v_pk_fma_f32 v[36:37], v[36:37], v[40:41], v[42:43] neg_lo:[0,0,1] neg_hi:[0,0,1]
	v_pk_fma_f32 v[34:35], v[34:35], v[44:45], v[50:51]
	v_pk_fma_f32 v[32:33], v[32:33], v[40:41], v[48:49]
.LBB0_251:
	v_mov_b32_e32 v40, v66
	v_mov_b32_e32 v41, v66
	v_pk_mul_f32 v[38:39], v[40:41], v[38:39]
	v_pk_mul_f32 v[36:37], v[66:67], v[36:37]
	v_pk_mul_f32 v[42:43], v[40:41], v[34:35]
	v_pk_mul_f32 v[34:35], v[66:67], v[32:33]
	v_cvt_pk_bf16_f32 v32, v36, v37
	v_cvt_pk_bf16_f32 v33, v38, v39
	v_cvt_pk_bf16_f32 v34, v34, v35
	v_cvt_pk_bf16_f32 v35, v42, v43
	s_nop 0
	v_permlane16_swap_b32_e32 v32, v34
	v_permlane16_swap_b32_e32 v33, v35
	global_store_dwordx4 v[96:97], v[32:35], off offset:256
	s_and_b64 vcc, exec, s[10:11]
	s_cbranch_vccnz .LBB0_253
	v_mov_b32_e32 v32, s21
	v_cndmask_b32_e64 v32, v140, v32, s[8:9]
	v_lshl_or_b32 v36, v32, 7, v146
	ds_read_b128 v[32:35], v36
	s_nop 0
	ds_read_b128 v[36:39], v36 offset:16
	s_waitcnt lgkmcnt(0)
	v_mov_b32_e32 v42, v33
	v_mov_b32_e32 v43, v35
	v_mov_b32_e32 v44, v37
	v_mov_b32_e32 v45, v39
	v_mov_b32_e32 v37, v38
	v_mov_b32_e32 v33, v34
	v_pk_mul_f32 v[34:35], v[24:25], v[42:43]
	v_pk_mul_f32 v[38:39], v[26:27], v[44:45]
	v_pk_mul_f32 v[42:43], v[28:29], v[42:43]
	v_pk_mul_f32 v[44:45], v[30:31], v[44:45]
	v_pk_fma_f32 v[30:31], v[30:31], v[36:37], v[38:39] neg_lo:[0,0,1] neg_hi:[0,0,1]
	v_pk_fma_f32 v[28:29], v[28:29], v[32:33], v[34:35] neg_lo:[0,0,1] neg_hi:[0,0,1]
	v_pk_fma_f32 v[26:27], v[26:27], v[36:37], v[44:45]
	v_pk_fma_f32 v[24:25], v[24:25], v[32:33], v[42:43]
.LBB0_253:
	v_pk_mul_f32 v[30:31], v[40:41], v[30:31]
	v_pk_mul_f32 v[28:29], v[66:67], v[28:29]
	v_pk_mul_f32 v[32:33], v[40:41], v[26:27]
	v_pk_mul_f32 v[26:27], v[66:67], v[24:25]
	v_cvt_pk_bf16_f32 v24, v28, v29
	v_cvt_pk_bf16_f32 v25, v30, v31
	v_cvt_pk_bf16_f32 v26, v26, v27
	v_cvt_pk_bf16_f32 v27, v32, v33
	s_nop 0
	v_permlane16_swap_b32_e32 v24, v26
	v_permlane16_swap_b32_e32 v25, v27
	global_store_dwordx4 v[88:89], v[24:27], off offset:256
	s_and_b64 vcc, exec, s[10:11]
	s_cbranch_vccnz .LBB0_255
	v_mov_b32_e32 v24, s21
	v_cndmask_b32_e64 v24, v142, v24, s[8:9]
	v_lshl_or_b32 v28, v24, 7, v146
	ds_read_b128 v[24:27], v28
	s_nop 0
	ds_read_b128 v[28:31], v28 offset:16
	s_waitcnt lgkmcnt(0)
	v_mov_b32_e32 v32, v25
	v_mov_b32_e32 v33, v27
	v_mov_b32_e32 v34, v29
	v_mov_b32_e32 v35, v31
	v_mov_b32_e32 v29, v30
	v_mov_b32_e32 v25, v26
	v_pk_mul_f32 v[26:27], v[16:17], v[32:33]
	v_pk_mul_f32 v[30:31], v[18:19], v[34:35]
	v_pk_mul_f32 v[32:33], v[20:21], v[32:33]
	v_pk_mul_f32 v[34:35], v[22:23], v[34:35]
	v_pk_fma_f32 v[22:23], v[22:23], v[28:29], v[30:31] neg_lo:[0,0,1] neg_hi:[0,0,1]
	v_pk_fma_f32 v[20:21], v[20:21], v[24:25], v[26:27] neg_lo:[0,0,1] neg_hi:[0,0,1]
	v_pk_fma_f32 v[18:19], v[18:19], v[28:29], v[34:35]
	v_pk_fma_f32 v[16:17], v[16:17], v[24:25], v[32:33]
.LBB0_255:
	v_mov_b32_e32 v24, v66
	v_mov_b32_e32 v25, v66
	v_pk_mul_f32 v[22:23], v[24:25], v[22:23]
	v_pk_mul_f32 v[20:21], v[66:67], v[20:21]
	v_pk_mul_f32 v[26:27], v[24:25], v[18:19]
	v_pk_mul_f32 v[18:19], v[66:67], v[16:17]
	v_cvt_pk_bf16_f32 v16, v20, v21
	v_cvt_pk_bf16_f32 v17, v22, v23
	v_cvt_pk_bf16_f32 v18, v18, v19
	v_cvt_pk_bf16_f32 v19, v26, v27
	s_nop 0
	v_permlane16_swap_b32_e32 v16, v18
	v_permlane16_swap_b32_e32 v17, v19
	global_store_dwordx4 v[80:81], v[16:19], off offset:256
	s_and_b64 vcc, exec, s[10:11]
	s_cbranch_vccnz .LBB0_257
	v_mov_b32_e32 v16, s21
	v_cndmask_b32_e64 v16, v143, v16, s[8:9]
	v_lshl_or_b32 v20, v16, 7, v146
	ds_read_b128 v[16:19], v20
	s_nop 0
	ds_read_b128 v[20:23], v20 offset:16
	s_waitcnt lgkmcnt(0)
	v_mov_b32_e32 v26, v17
	v_mov_b32_e32 v27, v19
	v_mov_b32_e32 v28, v21
	v_mov_b32_e32 v29, v23
	v_mov_b32_e32 v21, v22
	v_mov_b32_e32 v17, v18
	v_pk_mul_f32 v[18:19], v[8:9], v[26:27]
	v_pk_mul_f32 v[22:23], v[10:11], v[28:29]
	v_pk_mul_f32 v[26:27], v[12:13], v[26:27]
	v_pk_mul_f32 v[28:29], v[14:15], v[28:29]
	v_pk_fma_f32 v[14:15], v[14:15], v[20:21], v[22:23] neg_lo:[0,0,1] neg_hi:[0,0,1]
	v_pk_fma_f32 v[12:13], v[12:13], v[16:17], v[18:19] neg_lo:[0,0,1] neg_hi:[0,0,1]
	v_pk_fma_f32 v[10:11], v[10:11], v[20:21], v[28:29]
	v_pk_fma_f32 v[8:9], v[8:9], v[16:17], v[26:27]
.LBB0_257:
	v_pk_mul_f32 v[14:15], v[24:25], v[14:15]
	v_pk_mul_f32 v[12:13], v[66:67], v[12:13]
	v_pk_mul_f32 v[16:17], v[24:25], v[10:11]
	v_pk_mul_f32 v[10:11], v[66:67], v[8:9]
	v_cvt_pk_bf16_f32 v8, v12, v13
	v_cvt_pk_bf16_f32 v9, v14, v15
	v_cvt_pk_bf16_f32 v10, v10, v11
	v_cvt_pk_bf16_f32 v11, v16, v17
	s_nop 0
	v_permlane16_swap_b32_e32 v8, v10
	v_permlane16_swap_b32_e32 v9, v11
	global_store_dwordx4 v[72:73], v[8:11], off offset:256
	s_and_b64 vcc, exec, s[10:11]
	s_cbranch_vccnz .LBB0_259
	v_mov_b32_e32 v8, s21
	v_cndmask_b32_e64 v8, v144, v8, s[8:9]
	v_lshl_or_b32 v12, v8, 7, v146
	ds_read_b128 v[8:11], v12
	s_nop 0
	ds_read_b128 v[12:15], v12 offset:16
	s_waitcnt lgkmcnt(0)
	v_mov_b32_e32 v16, v9
	v_mov_b32_e32 v17, v11
	v_mov_b32_e32 v18, v13
	v_mov_b32_e32 v19, v15
	v_mov_b32_e32 v13, v14
	v_mov_b32_e32 v9, v10
	v_pk_mul_f32 v[10:11], v[0:1], v[16:17]
	v_pk_mul_f32 v[14:15], v[2:3], v[18:19]
	v_pk_mul_f32 v[16:17], v[4:5], v[16:17]
	v_pk_mul_f32 v[18:19], v[6:7], v[18:19]
	v_pk_fma_f32 v[6:7], v[6:7], v[12:13], v[14:15] neg_lo:[0,0,1] neg_hi:[0,0,1]
	v_pk_fma_f32 v[4:5], v[4:5], v[8:9], v[10:11] neg_lo:[0,0,1] neg_hi:[0,0,1]
	v_pk_fma_f32 v[2:3], v[2:3], v[12:13], v[18:19]
	v_pk_fma_f32 v[0:1], v[0:1], v[8:9], v[16:17]

.LBB0_286:
	s_add_u32 s18, s2, 0x1c000000
	s_addc_u32 s19, s3, 0
	s_lshl_b32 s43, s6, 6
	s_lshl_b32 s9, s6, 13
	s_lshl_b32 s6, s7, 5
	s_and_b32 s44, s6, 0x60
	s_add_i32 m0, s39, 0x18000
	v_lshl_add_u64 v[14:15], v[14:15], 0, s[90:91]
	s_lshl_b32 s24, s44, 7
	s_waitcnt vmcnt(2)
	s_barrier
	global_load_lds_dwordx4 v[14:15], off
	v_lshl_add_u64 v[10:11], v[10:11], 0, s[90:91]
	s_add_i32 m0, s39, 0x1a000
	s_add_i32 s45, s39, 0x8000
	s_add_i32 s46, s39, 0xa000
	global_load_lds_dwordx4 v[10:11], off
	v_lshl_add_u64 v[2:3], v[2:3], 0, s[90:91]
	s_mov_b32 m0, s45
	s_add_u32 s6, s34, 0x18080
	global_load_lds_dwordx4 v[2:3], off
	v_lshl_add_u64 v[2:3], v[6:7], 0, s[90:91]
	s_mov_b32 m0, s46
	s_addc_u32 s7, s35, 0
	global_load_lds_dwordx4 v[2:3], off
	s_add_i32 m0, s39, 0x1c000
	v_lshl_add_u64 v[2:3], s[6:7], 0, v[130:131]
	global_load_lds_dwordx4 v[2:3], off
	v_lshl_add_u64 v[2:3], s[6:7], 0, v[132:133]
	s_add_i32 m0, s39, 0x1e000
	v_and_b32_e32 v140, 15, v128
	global_load_lds_dwordx4 v[2:3], off
	v_bfe_u32 v142, v128, 4, 2
	v_lshlrev_b32_e32 v143, 2, v128
	s_cmpk_lt_u32 s8, 0x100
	v_and_b32_e32 v128, 16, v128
	s_movk_i32 s8, 0x180
	v_cmp_eq_u32_e32 vcc, 0, v128
	v_lshrrev_b32_e32 v134, 1, v134
	v_mul_lo_u32 v128, v135, s8
	v_mad_u64_u32 v[134:135], s[6:7], v134, s68, v[128:129]
	v_or_b32_e32 v128, v134, v145
	v_add_lshl_u32 v128, v128, v146, 1
	s_mov_b64 s[26:27], 0x18080
	v_lshlrev_b32_e32 v141, 4, v142
	v_lshl_add_u64 v[134:135], v[128:129], 0, s[26:27]
	v_lshrrev_b32_e32 v136, 1, v136
	v_mul_lo_u32 v128, v137, s8
	v_lshlrev_b32_e32 v147, 3, v142
	v_lshl_or_b32 v141, v140, 6, v141
	v_and_b32_e32 v143, 32, v143
	v_lshlrev_b32_e32 v142, 2, v142
	v_mad_u64_u32 v[136:137], s[6:7], v136, s68, v[128:129]
	v_bitop3_b32 v149, v141, s9, v143 bitop3:0xde
	v_bitop3_b32 v141, v141, s24, v143 bitop3:0xde
	s_waitcnt vmcnt(6)
	v_add_u32_e32 v143, 12, v142
	v_or_b32_e32 v128, v136, v138
	v_cndmask_b32_e32 v148, v143, v142, vcc
	v_add_lshl_u32 v128, v128, v139, 1
	v_mov_b32_e32 v125, v124
	v_mov_b32_e32 v126, v124
	v_mov_b32_e32 v127, v124
	v_mov_b32_e32 v121, v120
	v_mov_b32_e32 v122, v120
	v_mov_b32_e32 v123, v120
	v_mov_b32_e32 v117, v116
	v_mov_b32_e32 v118, v116
	v_mov_b32_e32 v119, v116
	v_mov_b32_e32 v113, v112
	v_mov_b32_e32 v114, v112
	v_mov_b32_e32 v115, v112
	v_mov_b32_e32 v109, v108
	v_mov_b32_e32 v110, v108
	v_mov_b32_e32 v111, v108
	v_mov_b32_e32 v105, v104
	v_mov_b32_e32 v106, v104
	v_mov_b32_e32 v107, v104
	v_mov_b32_e32 v101, v100
	v_mov_b32_e32 v102, v100
	v_mov_b32_e32 v103, v100
	v_mov_b32_e32 v97, v96
	v_mov_b32_e32 v98, v96
	v_mov_b32_e32 v99, v96
	v_mov_b32_e32 v61, v60
	v_mov_b32_e32 v62, v60
	v_mov_b32_e32 v63, v60
	v_mov_b32_e32 v57, v56
	v_mov_b32_e32 v58, v56
	v_mov_b32_e32 v59, v56
	v_mov_b32_e32 v53, v52
	v_mov_b32_e32 v54, v52
	v_mov_b32_e32 v55, v52
	v_mov_b32_e32 v49, v48
	v_mov_b32_e32 v50, v48
	v_mov_b32_e32 v51, v48
	v_mov_b32_e32 v45, v44
	v_mov_b32_e32 v46, v44
	v_mov_b32_e32 v47, v44
	v_mov_b32_e32 v41, v40
	v_mov_b32_e32 v42, v40
	v_mov_b32_e32 v43, v40
	v_mov_b32_e32 v37, v36
	v_mov_b32_e32 v38, v36
	v_mov_b32_e32 v39, v36
	v_mov_b32_e32 v33, v32
	v_mov_b32_e32 v34, v32
	v_mov_b32_e32 v35, v32
	v_mov_b32_e32 v93, v92
	v_mov_b32_e32 v94, v92
	v_mov_b32_e32 v95, v92
	v_mov_b32_e32 v89, v88
	v_mov_b32_e32 v90, v88
	v_mov_b32_e32 v91, v88
	v_mov_b32_e32 v85, v84
	v_mov_b32_e32 v86, v84
	v_mov_b32_e32 v87, v84
	v_mov_b32_e32 v81, v80
	v_mov_b32_e32 v82, v80
	v_mov_b32_e32 v83, v80
	v_mov_b32_e32 v77, v76
	v_mov_b32_e32 v78, v76
	v_mov_b32_e32 v79, v76
	v_mov_b32_e32 v73, v72
	v_mov_b32_e32 v74, v72
	v_mov_b32_e32 v75, v72
	v_mov_b32_e32 v69, v68
	v_mov_b32_e32 v70, v68
	v_mov_b32_e32 v71, v68
	v_mov_b32_e32 v65, v64
	v_mov_b32_e32 v66, v64
	v_mov_b32_e32 v67, v64
	v_mov_b32_e32 v29, v28
	v_mov_b32_e32 v30, v28
	v_mov_b32_e32 v31, v28
	v_mov_b32_e32 v25, v24
	v_mov_b32_e32 v26, v24
	v_mov_b32_e32 v27, v24
	v_mov_b32_e32 v21, v20
	v_mov_b32_e32 v22, v20
	v_mov_b32_e32 v23, v20
	v_mov_b32_e32 v17, v16
	v_mov_b32_e32 v18, v16
	v_mov_b32_e32 v19, v16
	v_mov_b32_e32 v13, v12
	v_mov_b32_e32 v14, v12
	v_mov_b32_e32 v15, v12
	v_mov_b32_e32 v9, v8
	v_mov_b32_e32 v10, v8
	v_mov_b32_e32 v11, v8
	v_mov_b32_e32 v5, v4
	v_mov_b32_e32 v6, v4
	v_mov_b32_e32 v7, v4
	v_mov_b32_e32 v1, v0
	v_mov_b32_e32 v2, v0
	v_mov_b32_e32 v3, v0
	s_cselect_b64 s[24:25], -1, 0
	s_mov_b32 s47, 0
	v_or_b32_e32 v142, 16, v140
	v_or_b32_e32 v143, 32, v140
	v_or_b32_e32 v144, 48, v140
	s_ashr_i32 s48, s63, 31
	s_ashr_i32 s49, s62, 31
	v_lshl_add_u64 v[136:137], v[128:129], 0, s[26:27]
	v_add_u32_e32 v145, 0, v149
	v_lshlrev_b32_e32 v128, 1, v148
	v_lshlrev_b32_e32 v146, 2, v147
	v_or_b32_e32 v146, 0x20000, v146
	s_barrier
	s_branch .LBB0_289

.LBB0_299:
	s_cmpk_lt_i32 s21, 0x80
	s_cselect_b64 s[34:35], -1, 0
	s_lshl_b32 s8, s20, 8
	s_or_b32 s36, s8, s44
	s_mul_hi_i32 s8, s36, 0x2aaaaaab
	s_lshr_b32 s9, s8, 31
	s_lshr_b32 s8, s8, 5
	s_add_i32 s8, s8, s9
	s_lshl_b32 s21, s21, 8
	s_mulk_i32 s8, 0xc0
	s_add_i32 s21, s21, s43
	s_sub_i32 s10, s36, s8
	s_cmpk_gt_i32 s10, 0x7f
	s_cselect_b64 s[8:9], -1, 0
	s_and_b64 s[30:31], s[34:35], s[8:9]
	s_bitcmp0_b32 s10, 5
	v_cndmask_b32_e64 v138, 0, 1, s[30:31]
	s_cselect_b64 s[8:9], -1, 0
	v_cmp_ne_u32_e64 s[10:11], 1, v138
	s_andn2_b64 vcc, exec, s[30:31]
	s_bfe_u32 s20, s21, 0x60006
	s_cbranch_vccnz .LBB0_301
	v_mov_b32_e32 v138, s20
	v_cndmask_b32_e64 v138, v140, v138, s[8:9]
	v_lshl_or_b32 v138, v138, 7, v146
	ds_read_b128 v[148:151], v138
	ds_read_b128 v[152:155], v138 offset:16
	s_waitcnt lgkmcnt(0)
	v_mov_b32_e32 v138, v149
	v_mov_b32_e32 v139, v151
	v_mov_b32_e32 v156, v153
	v_mov_b32_e32 v157, v155
	v_mov_b32_e32 v153, v154
	v_mov_b32_e32 v149, v150
	v_pk_mul_f32 v[150:151], v[120:121], v[138:139]
	v_pk_mul_f32 v[154:155], v[122:123], v[156:157]
	v_pk_mul_f32 v[138:139], v[124:125], v[138:139]
	v_pk_mul_f32 v[156:157], v[126:127], v[156:157]
	v_pk_fma_f32 v[126:127], v[126:127], v[152:153], v[154:155] neg_lo:[0,0,1] neg_hi:[0,0,1]
	v_pk_fma_f32 v[124:125], v[124:125], v[148:149], v[150:151] neg_lo:[0,0,1] neg_hi:[0,0,1]
	v_pk_fma_f32 v[122:123], v[122:123], v[152:153], v[156:157]
	v_pk_fma_f32 v[120:121], v[120:121], v[148:149], v[138:139]
.LBB0_301:
	s_cmpk_lt_i32 s36, 0x600
	s_cselect_b64 vcc, -1, 0
	v_cndmask_b32_e32 v138, 1.0, v235, vcc
	v_or_b32_e32 v139, s21, v140
	v_pk_mul_f32 v[124:125], v[138:139], v[124:125] op_sel_hi:[0,1]
	v_pk_mul_f32 v[120:121], v[138:139], v[120:121] op_sel_hi:[0,1]
	v_pk_mul_f32 v[148:149], v[138:139], v[122:123] op_sel_hi:[0,1]
	v_cvt_pk_bf16_f32 v122, v124, v125
	v_cvt_pk_bf16_f32 v124, v120, v121
	v_mov_b64_e32 v[120:121], s[18:19]
	s_ashr_i32 s37, s36, 31
	v_pk_mul_f32 v[126:127], v[138:139], v[126:127] op_sel_hi:[0,1]
	v_mad_i64_i32 v[120:121], s[30:31], v139, s81, v[120:121]
	v_cvt_pk_bf16_f32 v123, v126, v127
	v_cvt_pk_bf16_f32 v125, v148, v149
	v_lshl_add_u64 v[120:121], s[36:37], 1, v[120:121]
	v_permlane16_swap_b32_e32 v122, v124
	v_permlane16_swap_b32_e32 v123, v125
	v_lshl_add_u64 v[120:121], v[120:121], 0, v[128:129]
	global_store_dwordx4 v[120:121], v[122:125], off
	s_and_b64 vcc, exec, s[10:11]
	s_cbranch_vccnz .LBB0_303
	v_mov_b32_e32 v122, s20
	v_cndmask_b32_e64 v122, v142, v122, s[8:9]
	v_lshl_or_b32 v126, v122, 7, v146
	ds_read_b128 v[122:125], v126
	ds_read_b128 v[148:151], v126 offset:16
	s_waitcnt lgkmcnt(0)
	v_mov_b32_e32 v126, v123
	v_mov_b32_e32 v127, v125
	v_mov_b32_e32 v152, v149
	v_mov_b32_e32 v153, v151
	v_mov_b32_e32 v149, v150
	v_mov_b32_e32 v123, v124
	v_pk_mul_f32 v[124:125], v[112:113], v[126:127]
	v_pk_mul_f32 v[150:151], v[114:115], v[152:153]
	v_pk_mul_f32 v[126:127], v[116:117], v[126:127]
	v_pk_mul_f32 v[152:153], v[118:119], v[152:153]
	v_pk_fma_f32 v[118:119], v[118:119], v[148:149], v[150:151] neg_lo:[0,0,1] neg_hi:[0,0,1]
	v_pk_fma_f32 v[116:117], v[116:117], v[122:123], v[124:125] neg_lo:[0,0,1] neg_hi:[0,0,1]
	v_pk_fma_f32 v[114:115], v[114:115], v[148:149], v[152:153]
	v_pk_fma_f32 v[112:113], v[112:113], v[122:123], v[126:127]
.LBB0_303:
	v_mov_b32_e32 v139, v138
	v_mov_b32_e32 v122, v138
	v_mov_b32_e32 v123, v138
	v_pk_mul_f32 v[116:117], v[138:139], v[116:117]
	v_pk_mul_f32 v[112:113], v[138:139], v[112:113]
	v_or_b32_e32 v126, s21, v142
	v_pk_mul_f32 v[124:125], v[122:123], v[114:115]
	v_cvt_pk_bf16_f32 v114, v116, v117
	v_cvt_pk_bf16_f32 v116, v112, v113
	v_mov_b64_e32 v[112:113], s[18:19]
	v_pk_mul_f32 v[118:119], v[122:123], v[118:119]
	v_mad_i64_i32 v[112:113], s[30:31], v126, s81, v[112:113]
	v_cvt_pk_bf16_f32 v115, v118, v119
	v_cvt_pk_bf16_f32 v117, v124, v125
	v_lshl_add_u64 v[112:113], s[36:37], 1, v[112:113]
	v_permlane16_swap_b32_e32 v114, v116
	v_permlane16_swap_b32_e32 v115, v117
	v_lshl_add_u64 v[112:113], v[112:113], 0, v[128:129]
	global_store_dwordx4 v[112:113], v[114:117], off
	s_and_b64 vcc, exec, s[10:11]
	s_cbranch_vccnz .LBB0_305
	v_mov_b32_e32 v114, s20
	v_cndmask_b32_e64 v114, v143, v114, s[8:9]
	v_lshl_or_b32 v118, v114, 7, v146
	ds_read_b128 v[114:117], v118
	ds_read_b128 v[124:127], v118 offset:16
	s_waitcnt lgkmcnt(0)
	v_mov_b32_e32 v118, v115
	v_mov_b32_e32 v119, v117
	v_mov_b32_e32 v148, v125
	v_mov_b32_e32 v149, v127
	v_mov_b32_e32 v125, v126
	v_mov_b32_e32 v115, v116
	v_pk_mul_f32 v[116:117], v[104:105], v[118:119]
	v_pk_mul_f32 v[126:127], v[106:107], v[148:149]
	v_pk_mul_f32 v[118:119], v[108:109], v[118:119]
	v_pk_mul_f32 v[148:149], v[110:111], v[148:149]
	v_pk_fma_f32 v[110:111], v[110:111], v[124:125], v[126:127] neg_lo:[0,0,1] neg_hi:[0,0,1]
	v_pk_fma_f32 v[108:109], v[108:109], v[114:115], v[116:117] neg_lo:[0,0,1] neg_hi:[0,0,1]
	v_pk_fma_f32 v[106:107], v[106:107], v[124:125], v[148:149]
	v_pk_fma_f32 v[104:105], v[104:105], v[114:115], v[118:119]
.LBB0_305:
	v_pk_mul_f32 v[108:109], v[138:139], v[108:109]
	v_pk_mul_f32 v[104:105], v[138:139], v[104:105]
	v_or_b32_e32 v116, s21, v143
	v_pk_mul_f32 v[114:115], v[122:123], v[106:107]
	v_cvt_pk_bf16_f32 v106, v108, v109
	v_cvt_pk_bf16_f32 v108, v104, v105
	v_mov_b64_e32 v[104:105], s[18:19]
	v_pk_mul_f32 v[110:111], v[122:123], v[110:111]
	v_mad_i64_i32 v[104:105], s[30:31], v116, s81, v[104:105]
	v_cvt_pk_bf16_f32 v107, v110, v111
	v_cvt_pk_bf16_f32 v109, v114, v115
	v_lshl_add_u64 v[104:105], s[36:37], 1, v[104:105]
	v_permlane16_swap_b32_e32 v106, v108
	v_permlane16_swap_b32_e32 v107, v109
	v_lshl_add_u64 v[104:105], v[104:105], 0, v[128:129]
	global_store_dwordx4 v[104:105], v[106:109], off
	s_and_b64 vcc, exec, s[10:11]
	s_cbranch_vccnz .LBB0_307
	v_mov_b32_e32 v106, s20
	v_cndmask_b32_e64 v106, v144, v106, s[8:9]
	v_lshl_or_b32 v110, v106, 7, v146
	ds_read_b128 v[106:109], v110
	ds_read_b128 v[114:117], v110 offset:16
	s_waitcnt lgkmcnt(0)
	v_mov_b32_e32 v110, v107
	v_mov_b32_e32 v111, v109
	v_mov_b32_e32 v118, v115
	v_mov_b32_e32 v119, v117
	v_mov_b32_e32 v115, v116
	v_mov_b32_e32 v107, v108
	v_pk_mul_f32 v[108:109], v[96:97], v[110:111]
	v_pk_mul_f32 v[116:117], v[98:99], v[118:119]
	v_pk_mul_f32 v[110:111], v[100:101], v[110:111]
	v_pk_mul_f32 v[118:119], v[102:103], v[118:119]
	v_pk_fma_f32 v[102:103], v[102:103], v[114:115], v[116:117] neg_lo:[0,0,1] neg_hi:[0,0,1]
	v_pk_fma_f32 v[100:101], v[100:101], v[106:107], v[108:109] neg_lo:[0,0,1] neg_hi:[0,0,1]
	v_pk_fma_f32 v[98:99], v[98:99], v[114:115], v[118:119]
	v_pk_fma_f32 v[96:97], v[96:97], v[106:107], v[110:111]
.LBB0_307:
	v_mov_b32_e32 v106, v138
	v_mov_b32_e32 v107, v138
	v_pk_mul_f32 v[100:101], v[138:139], v[100:101]
	v_pk_mul_f32 v[96:97], v[138:139], v[96:97]
	v_or_b32_e32 v110, s21, v144
	v_pk_mul_f32 v[108:109], v[106:107], v[98:99]
	v_cvt_pk_bf16_f32 v98, v100, v101
	v_cvt_pk_bf16_f32 v100, v96, v97
	v_mov_b64_e32 v[96:97], s[18:19]
	v_pk_mul_f32 v[102:103], v[106:107], v[102:103]
	v_mad_i64_i32 v[96:97], s[30:31], v110, s81, v[96:97]
	v_cvt_pk_bf16_f32 v99, v102, v103
	v_cvt_pk_bf16_f32 v101, v108, v109
	v_lshl_add_u64 v[96:97], s[36:37], 1, v[96:97]
	v_permlane16_swap_b32_e32 v98, v100
	v_permlane16_swap_b32_e32 v99, v101
	v_lshl_add_u64 v[96:97], v[96:97], 0, v[128:129]
	global_store_dwordx4 v[96:97], v[98:101], off
	s_add_i32 s52, s21, 0x80
	s_and_b64 vcc, exec, s[10:11]
	s_bfe_u32 s21, s52, 0x60006
	s_cbranch_vccnz .LBB0_309
	v_mov_b32_e32 v98, s21
	v_cndmask_b32_e64 v98, v140, v98, s[8:9]
	v_lshl_or_b32 v102, v98, 7, v146
	ds_read_b128 v[98:101], v102
	ds_read_b128 v[108:111], v102 offset:16
	s_waitcnt lgkmcnt(0)
	v_mov_b32_e32 v102, v99
	v_mov_b32_e32 v103, v101
	v_mov_b32_e32 v114, v109
	v_mov_b32_e32 v115, v111
	v_mov_b32_e32 v109, v110
	v_mov_b32_e32 v99, v100
	v_pk_mul_f32 v[100:101], v[88:89], v[102:103]
	v_pk_mul_f32 v[110:111], v[90:91], v[114:115]
	v_pk_mul_f32 v[102:103], v[92:93], v[102:103]
	v_pk_mul_f32 v[114:115], v[94:95], v[114:115]
	v_pk_fma_f32 v[94:95], v[94:95], v[108:109], v[110:111] neg_lo:[0,0,1] neg_hi:[0,0,1]
	v_pk_fma_f32 v[92:93], v[92:93], v[98:99], v[100:101] neg_lo:[0,0,1] neg_hi:[0,0,1]
	v_pk_fma_f32 v[90:91], v[90:91], v[108:109], v[114:115]
	v_pk_fma_f32 v[88:89], v[88:89], v[98:99], v[102:103]
.LBB0_309:
	v_pk_mul_f32 v[92:93], v[138:139], v[92:93]
	v_pk_mul_f32 v[88:89], v[138:139], v[88:89]
	v_or_b32_e32 v100, s52, v140
	v_pk_mul_f32 v[98:99], v[106:107], v[90:91]
	v_cvt_pk_bf16_f32 v90, v92, v93
	v_cvt_pk_bf16_f32 v92, v88, v89
	v_mov_b64_e32 v[88:89], s[18:19]
	v_pk_mul_f32 v[94:95], v[106:107], v[94:95]
	v_mad_i64_i32 v[88:89], s[30:31], v100, s81, v[88:89]
	v_cvt_pk_bf16_f32 v91, v94, v95
	v_cvt_pk_bf16_f32 v93, v98, v99
	v_lshl_add_u64 v[88:89], s[36:37], 1, v[88:89]
	v_permlane16_swap_b32_e32 v90, v92
	v_permlane16_swap_b32_e32 v91, v93
	v_lshl_add_u64 v[88:89], v[88:89], 0, v[128:129]
	global_store_dwordx4 v[88:89], v[90:93], off
	s_and_b64 vcc, exec, s[10:11]
	s_cbranch_vccnz .LBB0_311
	v_mov_b32_e32 v90, s21
	v_cndmask_b32_e64 v90, v142, v90, s[8:9]
	v_lshl_or_b32 v94, v90, 7, v146
	ds_read_b128 v[90:93], v94
	ds_read_b128 v[98:101], v94 offset:16
	s_waitcnt lgkmcnt(0)
	v_mov_b32_e32 v94, v91
	v_mov_b32_e32 v95, v93
	v_mov_b32_e32 v102, v99
	v_mov_b32_e32 v103, v101
	v_mov_b32_e32 v99, v100
	v_mov_b32_e32 v91, v92
	v_pk_mul_f32 v[92:93], v[80:81], v[94:95]
	v_pk_mul_f32 v[100:101], v[82:83], v[102:103]
	v_pk_mul_f32 v[94:95], v[84:85], v[94:95]
	v_pk_mul_f32 v[102:103], v[86:87], v[102:103]
	v_pk_fma_f32 v[86:87], v[86:87], v[98:99], v[100:101] neg_lo:[0,0,1] neg_hi:[0,0,1]
	v_pk_fma_f32 v[84:85], v[84:85], v[90:91], v[92:93] neg_lo:[0,0,1] neg_hi:[0,0,1]
	v_pk_fma_f32 v[82:83], v[82:83], v[98:99], v[102:103]
	v_pk_fma_f32 v[80:81], v[80:81], v[90:91], v[94:95]
.LBB0_311:
	v_mov_b32_e32 v90, v138
	v_mov_b32_e32 v91, v138
	v_pk_mul_f32 v[84:85], v[138:139], v[84:85]
	v_pk_mul_f32 v[80:81], v[138:139], v[80:81]
	v_or_b32_e32 v94, s52, v142
	v_pk_mul_f32 v[92:93], v[90:91], v[82:83]
	v_cvt_pk_bf16_f32 v82, v84, v85
	v_cvt_pk_bf16_f32 v84, v80, v81
	v_mov_b64_e32 v[80:81], s[18:19]
	v_pk_mul_f32 v[86:87], v[90:91], v[86:87]
	v_mad_i64_i32 v[80:81], s[30:31], v94, s81, v[80:81]
	v_cvt_pk_bf16_f32 v83, v86, v87
	v_cvt_pk_bf16_f32 v85, v92, v93
	v_lshl_add_u64 v[80:81], s[36:37], 1, v[80:81]
	v_permlane16_swap_b32_e32 v82, v84
	v_permlane16_swap_b32_e32 v83, v85
	v_lshl_add_u64 v[80:81], v[80:81], 0, v[128:129]
	global_store_dwordx4 v[80:81], v[82:85], off
	s_and_b64 vcc, exec, s[10:11]
	s_cbranch_vccnz .LBB0_313
	v_mov_b32_e32 v82, s21
	v_cndmask_b32_e64 v82, v143, v82, s[8:9]
	v_lshl_or_b32 v86, v82, 7, v146
	ds_read_b128 v[82:85], v86
	ds_read_b128 v[92:95], v86 offset:16
	s_waitcnt lgkmcnt(0)
	v_mov_b32_e32 v86, v83
	v_mov_b32_e32 v87, v85
	v_mov_b32_e32 v98, v93
	v_mov_b32_e32 v99, v95
	v_mov_b32_e32 v93, v94
	v_mov_b32_e32 v83, v84
	v_pk_mul_f32 v[84:85], v[72:73], v[86:87]
	v_pk_mul_f32 v[94:95], v[74:75], v[98:99]
	v_pk_mul_f32 v[86:87], v[76:77], v[86:87]
	v_pk_mul_f32 v[98:99], v[78:79], v[98:99]
	v_pk_fma_f32 v[78:79], v[78:79], v[92:93], v[94:95] neg_lo:[0,0,1] neg_hi:[0,0,1]
	v_pk_fma_f32 v[76:77], v[76:77], v[82:83], v[84:85] neg_lo:[0,0,1] neg_hi:[0,0,1]
	v_pk_fma_f32 v[74:75], v[74:75], v[92:93], v[98:99]
	v_pk_fma_f32 v[72:73], v[72:73], v[82:83], v[86:87]
.LBB0_313:
	v_pk_mul_f32 v[76:77], v[138:139], v[76:77]
	v_pk_mul_f32 v[72:73], v[138:139], v[72:73]
	v_or_b32_e32 v84, s52, v143
	v_pk_mul_f32 v[82:83], v[90:91], v[74:75]
	v_cvt_pk_bf16_f32 v74, v76, v77
	v_cvt_pk_bf16_f32 v76, v72, v73
	v_mov_b64_e32 v[72:73], s[18:19]
	v_pk_mul_f32 v[78:79], v[90:91], v[78:79]
	v_mad_i64_i32 v[72:73], s[30:31], v84, s81, v[72:73]
	v_cvt_pk_bf16_f32 v75, v78, v79
	v_cvt_pk_bf16_f32 v77, v82, v83
	v_lshl_add_u64 v[72:73], s[36:37], 1, v[72:73]
	v_permlane16_swap_b32_e32 v74, v76
	v_permlane16_swap_b32_e32 v75, v77
	v_lshl_add_u64 v[72:73], v[72:73], 0, v[128:129]
	global_store_dwordx4 v[72:73], v[74:77], off
	s_and_b64 vcc, exec, s[10:11]
	s_cbranch_vccnz .LBB0_315
	v_mov_b32_e32 v74, s21
	v_cndmask_b32_e64 v74, v144, v74, s[8:9]
	v_lshl_or_b32 v78, v74, 7, v146
	ds_read_b128 v[74:77], v78
	ds_read_b128 v[82:85], v78 offset:16
	s_waitcnt lgkmcnt(0)
	v_mov_b32_e32 v78, v75
	v_mov_b32_e32 v79, v77
	v_mov_b32_e32 v86, v83
	v_mov_b32_e32 v87, v85
	v_mov_b32_e32 v83, v84
	v_mov_b32_e32 v75, v76
	v_pk_mul_f32 v[76:77], v[64:65], v[78:79]
	v_pk_mul_f32 v[84:85], v[66:67], v[86:87]
	v_pk_mul_f32 v[78:79], v[68:69], v[78:79]
	v_pk_mul_f32 v[86:87], v[70:71], v[86:87]
	v_pk_fma_f32 v[70:71], v[70:71], v[82:83], v[84:85] neg_lo:[0,0,1] neg_hi:[0,0,1]
	v_pk_fma_f32 v[68:69], v[68:69], v[74:75], v[76:77] neg_lo:[0,0,1] neg_hi:[0,0,1]
	v_pk_fma_f32 v[66:67], v[66:67], v[82:83], v[86:87]
	v_pk_fma_f32 v[64:65], v[64:65], v[74:75], v[78:79]
.LBB0_315:
	v_mov_b32_e32 v74, v138
	v_mov_b32_e32 v75, v138
	v_pk_mul_f32 v[68:69], v[138:139], v[68:69]
	v_pk_mul_f32 v[64:65], v[138:139], v[64:65]
	v_or_b32_e32 v76, s52, v144
	v_pk_mul_f32 v[70:71], v[74:75], v[70:71]
	v_pk_mul_f32 v[74:75], v[74:75], v[66:67]
	v_cvt_pk_bf16_f32 v66, v68, v69
	v_cvt_pk_bf16_f32 v68, v64, v65
	v_mov_b64_e32 v[64:65], s[18:19]
	v_mad_i64_i32 v[64:65], s[8:9], v76, s81, v[64:65]
	v_lshl_add_u64 v[64:65], s[36:37], 1, v[64:65]
	s_bitset1_b32 s36, 7
	s_mul_hi_i32 s8, s36, 0x2aaaaaab
	s_lshr_b32 s9, s8, 31
	s_lshr_b32 s8, s8, 5
	s_add_i32 s8, s8, s9
	s_mulk_i32 s8, 0xc0
	v_cvt_pk_bf16_f32 v67, v70, v71
	v_cvt_pk_bf16_f32 v69, v74, v75
	s_sub_i32 s10, s36, s8
	v_permlane16_swap_b32_e32 v66, v68
	v_permlane16_swap_b32_e32 v67, v69
	v_lshl_add_u64 v[64:65], v[64:65], 0, v[128:129]
	s_cmpk_gt_i32 s10, 0x7f
	global_store_dwordx4 v[64:65], v[66:69], off
	s_cselect_b64 s[8:9], -1, 0
	s_and_b64 s[30:31], s[34:35], s[8:9]
	s_bitcmp0_b32 s10, 5
	v_cndmask_b32_e64 v66, 0, 1, s[30:31]
	s_cselect_b64 s[8:9], -1, 0
	v_cmp_ne_u32_e64 s[10:11], 1, v66
	s_andn2_b64 vcc, exec, s[30:31]
	s_cbranch_vccnz .LBB0_317
	v_mov_b32_e32 v66, s20
	v_cndmask_b32_e64 v66, v140, v66, s[8:9]
	v_lshl_or_b32 v70, v66, 7, v146
	ds_read_b128 v[66:69], v70
	ds_read_b128 v[74:77], v70 offset:16
	s_waitcnt lgkmcnt(0)
	v_mov_b32_e32 v70, v67
	v_mov_b32_e32 v71, v69
	v_mov_b32_e32 v78, v75
	v_mov_b32_e32 v79, v77
	v_mov_b32_e32 v75, v76
	v_mov_b32_e32 v67, v68
	v_pk_mul_f32 v[68:69], v[56:57], v[70:71]
	v_pk_mul_f32 v[76:77], v[58:59], v[78:79]
	v_pk_mul_f32 v[70:71], v[60:61], v[70:71]
	v_pk_mul_f32 v[78:79], v[62:63], v[78:79]
	v_pk_fma_f32 v[62:63], v[62:63], v[74:75], v[76:77] neg_lo:[0,0,1] neg_hi:[0,0,1]
	v_pk_fma_f32 v[60:61], v[60:61], v[66:67], v[68:69] neg_lo:[0,0,1] neg_hi:[0,0,1]
	v_pk_fma_f32 v[58:59], v[58:59], v[74:75], v[78:79]
	v_pk_fma_f32 v[56:57], v[56:57], v[66:67], v[70:71]
.LBB0_317:
	s_cmpk_lt_i32 s36, 0x600
	s_cselect_b64 vcc, -1, 0
	v_cndmask_b32_e32 v66, 1.0, v235, vcc
	v_pk_mul_f32 v[62:63], v[66:67], v[62:63] op_sel_hi:[0,1]
	v_pk_mul_f32 v[60:61], v[66:67], v[60:61] op_sel_hi:[0,1]
	v_pk_mul_f32 v[68:69], v[66:67], v[58:59] op_sel_hi:[0,1]
	v_pk_mul_f32 v[58:59], v[66:67], v[56:57] op_sel_hi:[0,1]
	v_cvt_pk_bf16_f32 v56, v60, v61
	v_cvt_pk_bf16_f32 v57, v62, v63
	v_cvt_pk_bf16_f32 v58, v58, v59
	v_cvt_pk_bf16_f32 v59, v68, v69
	s_nop 0
	v_permlane16_swap_b32_e32 v56, v58
	v_permlane16_swap_b32_e32 v57, v59
	global_store_dwordx4 v[120:121], v[56:59], off offset:256
	s_and_b64 vcc, exec, s[10:11]
	s_cbranch_vccnz .LBB0_319
	v_mov_b32_e32 v56, s20
	v_cndmask_b32_e64 v56, v142, v56, s[8:9]
	v_lshl_or_b32 v60, v56, 7, v146
	ds_read_b128 v[56:59], v60
	s_nop 0
	ds_read_b128 v[60:63], v60 offset:16
	s_waitcnt lgkmcnt(0)
	v_mov_b32_e32 v68, v57
	v_mov_b32_e32 v69, v59
	v_mov_b32_e32 v70, v61
	v_mov_b32_e32 v71, v63
	v_mov_b32_e32 v61, v62
	v_mov_b32_e32 v57, v58
	v_pk_mul_f32 v[58:59], v[48:49], v[68:69]
	v_pk_mul_f32 v[62:63], v[50:51], v[70:71]
	v_pk_mul_f32 v[68:69], v[52:53], v[68:69]
	v_pk_mul_f32 v[70:71], v[54:55], v[70:71]
	v_pk_fma_f32 v[54:55], v[54:55], v[60:61], v[62:63] neg_lo:[0,0,1] neg_hi:[0,0,1]
	v_pk_fma_f32 v[52:53], v[52:53], v[56:57], v[58:59] neg_lo:[0,0,1] neg_hi:[0,0,1]
	v_pk_fma_f32 v[50:51], v[50:51], v[60:61], v[70:71]
	v_pk_fma_f32 v[48:49], v[48:49], v[56:57], v[68:69]

.LBB0_456:
	s_lshl_b64 s[8:9], s[8:9], 2
	s_add_u32 s8, s89, s8
	s_addc_u32 s9, s52, s9
	v_lshl_or_b32 v168, s58, 8, v177
	v_lshlrev_b32_e32 v168, 2, v168
	s_lshl_b32 s5, s23, 8
	v_add_u32_e32 v128, s5, v172
	s_cmp_lg_u32 s22, 0
	s_cbranch_scc1 .Lresid_split
	global_load_dwordx4 v[142:145], v168, s[8:9]
	global_load_dwordx4 v[138:141], v168, s[8:9] offset:16
	global_load_dwordx4 v[134:137], v168, s[8:9] offset:512
	global_load_dwordx4 v[130:133], v168, s[8:9] offset:528
	v_lshl_add_u32 v128, v128, 12, v168
	v_mov_b32_e32 v170, v128
	global_load_dwordx4 v[198:201], v170, s[24:25]
	global_load_dwordx4 v[202:205], v170, s[24:25] offset:16
	global_load_dwordx4 v[206:209], v170, s[24:25] offset:512
	global_load_dwordx4 v[210:213], v170, s[24:25] offset:528
	v_add_u32_e32 v170, 0x10000, v128
	global_load_dwordx4 v[214:217], v170, s[24:25]
	global_load_dwordx4 v[218:221], v170, s[24:25] offset:16
	global_load_dwordx4 v[222:225], v170, s[24:25] offset:512
	global_load_dwordx4 v[226:229], v170, s[24:25] offset:528
	v_add_u32_e32 v170, 0x20000, v128
	global_load_dwordx4 v[238:241], v170, s[24:25]
	global_load_dwordx4 v[242:245], v170, s[24:25] offset:16
	global_load_dwordx4 v[246:249], v170, s[24:25] offset:512
	global_load_dwordx4 v[250:253], v170, s[24:25] offset:528
	v_add_u32_e32 v170, 0x30000, v128
	global_load_dwordx4 v[158:161], v170, s[24:25]
	global_load_dwordx4 v[162:165], v170, s[24:25] offset:16
	s_waitcnt vmcnt(13)
	v_pk_mul_f32 v[142:143], s[28:29], v[142:143]
	v_pk_mul_f32 v[144:145], s[28:29], v[144:145]
	v_pk_mul_f32 v[138:139], s[28:29], v[138:139]
	v_pk_mul_f32 v[140:141], s[28:29], v[140:141]
	v_pk_mul_f32 v[134:135], s[28:29], v[134:135]
	v_pk_mul_f32 v[136:137], s[28:29], v[136:137]
	v_pk_mul_f32 v[130:131], s[28:29], v[130:131]
	v_pk_mul_f32 v[132:133], s[28:29], v[132:133]
	v_pk_fma_f32 v[124:125], v[124:125], v[142:143], v[198:199]
	v_pk_fma_f32 v[126:127], v[126:127], v[144:145], v[200:201]
	v_mov_b32_e32 v171, v128
	global_store_dwordx4 v171, v[124:127], s[24:25]
	global_load_dwordx4 v[198:201], v170, s[24:25] offset:512
	s_waitcnt vmcnt(14)
	v_pk_fma_f32 v[120:121], v[120:121], v[138:139], v[202:203]
	v_pk_fma_f32 v[122:123], v[122:123], v[140:141], v[204:205]
	global_store_dwordx4 v171, v[120:123], s[24:25] offset:16
	global_load_dwordx4 v[202:205], v170, s[24:25] offset:528
	s_waitcnt vmcnt(15)
	v_pk_fma_f32 v[116:117], v[116:117], v[134:135], v[206:207]
	v_pk_fma_f32 v[118:119], v[118:119], v[136:137], v[208:209]
	global_store_dwordx4 v171, v[116:119], s[24:25] offset:512
	v_add_u32_e32 v170, 0x80000, v128
	global_load_dwordx4 v[206:209], v170, s[24:25]
	s_waitcnt vmcnt(16)
	v_pk_fma_f32 v[112:113], v[112:113], v[130:131], v[210:211]
	v_pk_fma_f32 v[114:115], v[114:115], v[132:133], v[212:213]
	global_store_dwordx4 v171, v[112:115], s[24:25] offset:528
	global_load_dwordx4 v[210:213], v170, s[24:25] offset:16
	s_waitcnt vmcnt(17)
	v_pk_fma_f32 v[108:109], v[108:109], v[142:143], v[214:215]
	v_pk_fma_f32 v[110:111], v[110:111], v[144:145], v[216:217]
	v_add_u32_e32 v171, 0x10000, v128
	global_store_dwordx4 v171, v[108:111], s[24:25]
	global_load_dwordx4 v[214:217], v170, s[24:25] offset:512
	s_waitcnt vmcnt(18)
	v_pk_fma_f32 v[104:105], v[104:105], v[138:139], v[218:219]
	v_pk_fma_f32 v[106:107], v[106:107], v[140:141], v[220:221]
	global_store_dwordx4 v171, v[104:107], s[24:25] offset:16
	global_load_dwordx4 v[218:221], v170, s[24:25] offset:528
	s_waitcnt vmcnt(19)
	v_pk_fma_f32 v[100:101], v[100:101], v[134:135], v[222:223]
	v_pk_fma_f32 v[102:103], v[102:103], v[136:137], v[224:225]
	global_store_dwordx4 v171, v[100:103], s[24:25] offset:512
	v_add_u32_e32 v170, 0x90000, v128
	global_load_dwordx4 v[222:225], v170, s[24:25]
	s_waitcnt vmcnt(20)
	v_pk_fma_f32 v[96:97], v[96:97], v[130:131], v[226:227]
	v_pk_fma_f32 v[98:99], v[98:99], v[132:133], v[228:229]
	global_store_dwordx4 v171, v[96:99], s[24:25] offset:528
	global_load_dwordx4 v[226:229], v170, s[24:25] offset:16
	s_waitcnt vmcnt(21)
	v_pk_fma_f32 v[92:93], v[92:93], v[142:143], v[238:239]
	v_pk_fma_f32 v[94:95], v[94:95], v[144:145], v[240:241]
	v_add_u32_e32 v171, 0x20000, v128
	global_store_dwordx4 v171, v[92:95], s[24:25]
	global_load_dwordx4 v[238:241], v170, s[24:25] offset:512
	s_waitcnt vmcnt(22)
	v_pk_fma_f32 v[88:89], v[88:89], v[138:139], v[242:243]
	v_pk_fma_f32 v[90:91], v[90:91], v[140:141], v[244:245]
	global_store_dwordx4 v171, v[88:91], s[24:25] offset:16
	global_load_dwordx4 v[242:245], v170, s[24:25] offset:528
	s_waitcnt vmcnt(23)
	v_pk_fma_f32 v[84:85], v[84:85], v[134:135], v[246:247]
	v_pk_fma_f32 v[86:87], v[86:87], v[136:137], v[248:249]
	global_store_dwordx4 v171, v[84:87], s[24:25] offset:512
	v_add_u32_e32 v170, 0xa0000, v128
	global_load_dwordx4 v[246:249], v170, s[24:25]
	s_waitcnt vmcnt(24)
	v_pk_fma_f32 v[80:81], v[80:81], v[130:131], v[250:251]
	v_pk_fma_f32 v[82:83], v[82:83], v[132:133], v[252:253]
	global_store_dwordx4 v171, v[80:83], s[24:25] offset:528
	global_load_dwordx4 v[250:253], v170, s[24:25] offset:16
	s_waitcnt vmcnt(25)
	v_pk_fma_f32 v[76:77], v[76:77], v[142:143], v[158:159]
	v_pk_fma_f32 v[78:79], v[78:79], v[144:145], v[160:161]
	v_add_u32_e32 v171, 0x30000, v128
	global_store_dwordx4 v171, v[76:79], s[24:25]
	global_load_dwordx4 v[158:161], v170, s[24:25] offset:512
	s_waitcnt vmcnt(26)
	v_pk_fma_f32 v[72:73], v[72:73], v[138:139], v[162:163]
	v_pk_fma_f32 v[74:75], v[74:75], v[140:141], v[164:165]
	global_store_dwordx4 v171, v[72:75], s[24:25] offset:16
	global_load_dwordx4 v[162:165], v170, s[24:25] offset:528
	s_waitcnt vmcnt(26)
	v_pk_fma_f32 v[68:69], v[68:69], v[134:135], v[198:199]
	v_pk_fma_f32 v[70:71], v[70:71], v[136:137], v[200:201]
	global_store_dwordx4 v171, v[68:71], s[24:25] offset:512
	v_add_u32_e32 v170, 0xb0000, v128
	global_load_dwordx4 v[198:201], v170, s[24:25]
	s_waitcnt vmcnt(26)
	v_pk_fma_f32 v[64:65], v[64:65], v[130:131], v[202:203]
	v_pk_fma_f32 v[66:67], v[66:67], v[132:133], v[204:205]
	global_store_dwordx4 v171, v[64:67], s[24:25] offset:528
	global_load_dwordx4 v[202:205], v170, s[24:25] offset:16
	s_waitcnt vmcnt(26)
	v_pk_fma_f32 v[60:61], v[60:61], v[142:143], v[206:207]
	v_pk_fma_f32 v[62:63], v[62:63], v[144:145], v[208:209]
	v_add_u32_e32 v171, 0x80000, v128
	global_store_dwordx4 v171, v[60:63], s[24:25]
	global_load_dwordx4 v[206:209], v170, s[24:25] offset:512
	s_waitcnt vmcnt(26)
	v_pk_fma_f32 v[56:57], v[56:57], v[138:139], v[210:211]
	v_pk_fma_f32 v[58:59], v[58:59], v[140:141], v[212:213]
	global_store_dwordx4 v171, v[56:59], s[24:25] offset:16
	global_load_dwordx4 v[210:213], v170, s[24:25] offset:528
	s_waitcnt vmcnt(26)
	v_pk_fma_f32 v[52:53], v[52:53], v[134:135], v[214:215]
	v_pk_fma_f32 v[54:55], v[54:55], v[136:137], v[216:217]
	global_store_dwordx4 v171, v[52:55], s[24:25] offset:512
	s_waitcnt vmcnt(25)
	v_pk_fma_f32 v[48:49], v[48:49], v[130:131], v[218:219]
	v_pk_fma_f32 v[50:51], v[50:51], v[132:133], v[220:221]
	global_store_dwordx4 v171, v[48:51], s[24:25] offset:528
	s_waitcnt vmcnt(24)
	v_pk_fma_f32 v[44:45], v[44:45], v[142:143], v[222:223]
	v_pk_fma_f32 v[46:47], v[46:47], v[144:145], v[224:225]
	v_add_u32_e32 v171, 0x90000, v128
	global_store_dwordx4 v171, v[44:47], s[24:25]
	s_waitcnt vmcnt(23)
	v_pk_fma_f32 v[40:41], v[40:41], v[138:139], v[226:227]
	v_pk_fma_f32 v[42:43], v[42:43], v[140:141], v[228:229]
	global_store_dwordx4 v171, v[40:43], s[24:25] offset:16
	s_waitcnt vmcnt(22)
	v_pk_fma_f32 v[36:37], v[36:37], v[134:135], v[238:239]
	v_pk_fma_f32 v[38:39], v[38:39], v[136:137], v[240:241]
	global_store_dwordx4 v171, v[36:39], s[24:25] offset:512
	s_waitcnt vmcnt(21)
	v_pk_fma_f32 v[32:33], v[32:33], v[130:131], v[242:243]
	v_pk_fma_f32 v[34:35], v[34:35], v[132:133], v[244:245]
	global_store_dwordx4 v171, v[32:35], s[24:25] offset:528
	s_waitcnt vmcnt(20)
	v_pk_fma_f32 v[28:29], v[28:29], v[142:143], v[246:247]
	v_pk_fma_f32 v[30:31], v[30:31], v[144:145], v[248:249]
	v_add_u32_e32 v171, 0xa0000, v128
	global_store_dwordx4 v171, v[28:31], s[24:25]
	s_waitcnt vmcnt(19)
	v_pk_fma_f32 v[24:25], v[24:25], v[138:139], v[250:251]
	v_pk_fma_f32 v[26:27], v[26:27], v[140:141], v[252:253]
	global_store_dwordx4 v171, v[24:27], s[24:25] offset:16
	s_waitcnt vmcnt(18)
	v_pk_fma_f32 v[20:21], v[20:21], v[134:135], v[158:159]
	v_pk_fma_f32 v[22:23], v[22:23], v[136:137], v[160:161]
	global_store_dwordx4 v171, v[20:23], s[24:25] offset:512
	s_waitcnt vmcnt(17)
	v_pk_fma_f32 v[16:17], v[16:17], v[130:131], v[162:163]
	v_pk_fma_f32 v[18:19], v[18:19], v[132:133], v[164:165]
	global_store_dwordx4 v171, v[16:19], s[24:25] offset:528
	s_waitcnt vmcnt(16)
	v_pk_fma_f32 v[12:13], v[12:13], v[142:143], v[198:199]
	v_pk_fma_f32 v[14:15], v[14:15], v[144:145], v[200:201]
	v_add_u32_e32 v171, 0xb0000, v128
	global_store_dwordx4 v171, v[12:15], s[24:25]
	s_waitcnt vmcnt(15)
	v_pk_fma_f32 v[8:9], v[8:9], v[138:139], v[202:203]
	v_pk_fma_f32 v[10:11], v[10:11], v[140:141], v[204:205]
	global_store_dwordx4 v171, v[8:11], s[24:25] offset:16
	s_waitcnt vmcnt(14)
	v_pk_fma_f32 v[4:5], v[4:5], v[134:135], v[206:207]
	v_pk_fma_f32 v[6:7], v[6:7], v[136:137], v[208:209]
	global_store_dwordx4 v171, v[4:7], s[24:25] offset:512
	s_waitcnt vmcnt(13)
	v_pk_fma_f32 v[0:1], v[0:1], v[130:131], v[210:211]
	v_pk_fma_f32 v[2:3], v[2:3], v[132:133], v[212:213]
	global_store_dwordx4 v171, v[0:3], s[24:25] offset:528
	s_branch .Lresid_done
.Lresid_split:
	s_lshl_b32 s30, s22, 23
	s_add_u32 s30, s30, 0x18400000
	s_add_u32 s30, s24, s30
	s_addc_u32 s31, s25, 0
	v_add_u32_e32 v128, 0xffff8000, v128
	v_lshl_add_u32 v128, v128, 12, v168
	v_mov_b32_e32 v171, v128
	global_store_dwordx4 v171, v[124:127], s[30:31]
	global_store_dwordx4 v171, v[120:123], s[30:31] offset:16
	global_store_dwordx4 v171, v[116:119], s[30:31] offset:512
	global_store_dwordx4 v171, v[112:115], s[30:31] offset:528
	v_add_u32_e32 v171, 0x10000, v128
	global_store_dwordx4 v171, v[108:111], s[30:31]
	global_store_dwordx4 v171, v[104:107], s[30:31] offset:16
	global_store_dwordx4 v171, v[100:103], s[30:31] offset:512
	global_store_dwordx4 v171, v[96:99], s[30:31] offset:528
	v_add_u32_e32 v171, 0x20000, v128
	global_store_dwordx4 v171, v[92:95], s[30:31]
	global_store_dwordx4 v171, v[88:91], s[30:31] offset:16
	global_store_dwordx4 v171, v[84:87], s[30:31] offset:512
	global_store_dwordx4 v171, v[80:83], s[30:31] offset:528
	v_add_u32_e32 v171, 0x30000, v128
	global_store_dwordx4 v171, v[76:79], s[30:31]
	global_store_dwordx4 v171, v[72:75], s[30:31] offset:16
	global_store_dwordx4 v171, v[68:71], s[30:31] offset:512
	global_store_dwordx4 v171, v[64:67], s[30:31] offset:528
	v_add_u32_e32 v171, 0x80000, v128
	global_store_dwordx4 v171, v[60:63], s[30:31]
	global_store_dwordx4 v171, v[56:59], s[30:31] offset:16
	global_store_dwordx4 v171, v[52:55], s[30:31] offset:512
	global_store_dwordx4 v171, v[48:51], s[30:31] offset:528
	v_add_u32_e32 v171, 0x90000, v128
	global_store_dwordx4 v171, v[44:47], s[30:31]
	global_store_dwordx4 v171, v[40:43], s[30:31] offset:16
	global_store_dwordx4 v171, v[36:39], s[30:31] offset:512
	global_store_dwordx4 v171, v[32:35], s[30:31] offset:528
	v_add_u32_e32 v171, 0xa0000, v128
	global_store_dwordx4 v171, v[28:31], s[30:31]
	global_store_dwordx4 v171, v[24:27], s[30:31] offset:16
	global_store_dwordx4 v171, v[20:23], s[30:31] offset:512
	global_store_dwordx4 v171, v[16:19], s[30:31] offset:528
	v_add_u32_e32 v171, 0xb0000, v128
	global_store_dwordx4 v171, v[12:15], s[30:31]
	global_store_dwordx4 v171, v[8:11], s[30:31] offset:16
	global_store_dwordx4 v171, v[4:7], s[30:31] offset:512
	global_store_dwordx4 v171, v[0:3], s[30:31] offset:528
.Lresid_done:
.LBB0_621:
	s_and_b64 vcc, exec, s[6:7]
	s_mov_b64 s[6:7], -1
	s_cbranch_vccnz .LBB0_432
	s_andn2_b64 vcc, exec, s[16:17]
	v_mov_b32 v124, 0
	v_mov_b32 v120, 0
	v_mov_b32 v108, 0
	v_mov_b32 v104, 0
	v_mov_b32 v92, 0
	v_mov_b32 v88, 0
	v_mov_b32 v76, 0
	v_mov_b32 v72, 0
	v_mov_b32 v116, 0
	v_mov_b32 v112, 0
	v_mov_b32 v100, 0
	v_mov_b32 v96, 0
	v_mov_b32 v84, 0
	v_mov_b32 v80, 0
	v_mov_b32 v68, 0
	v_mov_b32 v64, 0
	v_mov_b32 v60, 0
	v_mov_b32 v56, 0
	v_mov_b32 v44, 0
	v_mov_b32 v40, 0
	v_mov_b32 v28, 0
	v_mov_b32 v24, 0
	v_mov_b32 v12, 0
	v_mov_b32 v8, 0
	v_mov_b32 v52, 0
	v_mov_b32 v48, 0
	v_mov_b32 v36, 0
	v_mov_b32 v32, 0
	v_mov_b32 v20, 0
	v_mov_b32 v16, 0
	v_mov_b32 v4, 0
	v_mov_b32 v0, 0
	s_cbranch_vccnz .LBB0_431
	s_barrier
	s_branch .LBB0_431
